# FRes epilogues (w_out, ff2): f32 residual-stream stores marked nt (next read is a full phase later)
# baseline (speedup 1.0000x reference)
.LBB0_1063:
	v_lshl_add_u32 v188, s25, 8, v246
	s_add_u32 s54, s10, 0x2a00000
	v_ashrrev_i32_e32 v189, 31, v188
	s_addc_u32 s55, s11, 0
	v_lshlrev_b64 v[216:217], 11, v[188:189]
	v_lshl_add_u64 v[220:221], s[54:55], 0, v[216:217]
	v_lshlrev_b64 v[160:161], 1, v[192:193]
	v_lshl_add_u64 v[226:227], v[220:221], 0, v[160:161]
	s_waitcnt lgkmcnt(0)
	s_mov_b32 s101, 0
	s_mov_b32 s100, 0x8000
	v_lshl_add_u64 v[162:163], v[226:227], 0, s[100:101]
	s_mov_b32 s100, 0x10000
	v_lshl_add_u64 v[168:169], v[226:227], 0, s[100:101]
	s_mov_b32 s100, 0x18000
	v_lshl_add_u64 v[172:173], v[226:227], 0, s[100:101]
	global_load_dwordx4 v[0:3], v[226:227], off
	global_load_dwordx4 v[4:7], v[162:163], off
	global_load_dwordx4 v[8:11], v[168:169], off
	global_load_dwordx4 v[12:15], v[172:173], off
	global_load_dwordx4 v[16:19], v[226:227], off offset:256
	global_load_dwordx4 v[20:23], v[162:163], off offset:256
	global_load_dwordx4 v[24:27], v[168:169], off offset:256
	global_load_dwordx4 v[28:31], v[172:173], off offset:256
	v_or_b32_e32 v194, 16, v188
	v_ashrrev_i32_e32 v195, 31, v194
	v_lshl_add_u64 v[190:191], s[54:55], 0, v[160:161]
	v_lshlrev_b64 v[224:225], 11, v[194:195]
	v_lshl_add_u64 v[230:231], v[190:191], 0, v[224:225]
	v_lshl_add_u64 v[216:217], v[190:191], 0, v[216:217]
	v_or_b32_e32 v222, 0x80, v192
	v_ashrrev_i32_e32 v223, 31, v222
	s_lshl_b32 s12, s24, 3
	s_or_b32 s12, s12, s80
	s_ashr_i32 s13, s12, 31
	s_lshl_b64 s[12:13], s[12:13], 2
	s_add_u32 s10, s10, s12
	s_addc_u32 s11, s11, s13
	s_add_u32 s50, s10, 0xeb80000
	s_addc_u32 s51, s11, 0
	s_waitcnt vmcnt(7)
	s_nop 1
	v_mov_b32_e32 v198, v0
	v_mov_b32_e32 v199, v1
	v_mov_b32_e32 v200, v2
	v_mov_b32_e32 v201, v3
	v_lshlrev_b32_e32 v168, 16, v198
	v_and_b32_e32 v169, 0xffff0000, v198
	v_lshlrev_b32_e32 v172, 16, v199
	v_and_b32_e32 v173, 0xffff0000, v199
	v_sub_f32_e32 v199, v173, v208
	v_sub_f32_e32 v198, v172, v208
	v_sub_f32_e32 v213, v169, v208
	v_sub_f32_e32 v212, v168, v208
	v_pk_mul_f32 v[212:213], v[210:211], v[212:213] op_sel_hi:[0,1]
	v_pk_mul_f32 v[198:199], v[210:211], v[198:199] op_sel_hi:[0,1]
	v_pk_fma_f32 v[198:199], v[90:91], v[198:199], v[94:95]
	v_pk_fma_f32 v[212:213], v[88:89], v[212:213], v[92:93]
	v_cndmask_b32_e64 v199, v199, v173, s[30:31]
	v_cndmask_b32_e64 v213, v213, v169, s[30:31]
	v_cndmask_b32_e64 v212, v212, v168, s[30:31]
	v_cndmask_b32_e64 v198, v198, v172, s[30:31]
	v_lshlrev_b32_e32 v168, 16, v200
	v_and_b32_e32 v169, 0xffff0000, v200
	v_lshlrev_b32_e32 v172, 16, v201
	v_and_b32_e32 v173, 0xffff0000, v201
	v_pk_fma_f32 v[218:219], v[198:199], s[70:71], v[158:159] op_sel_hi:[1,0,1]
	v_pk_fma_f32 v[228:229], v[212:213], s[70:71], v[156:157] op_sel_hi:[1,0,1]
	v_sub_f32_e32 v157, v173, v208
	v_sub_f32_e32 v156, v172, v208
	v_sub_f32_e32 v159, v169, v208
	v_sub_f32_e32 v158, v168, v208
	v_pk_mul_f32 v[158:159], v[210:211], v[158:159] op_sel_hi:[0,1]
	v_pk_mul_f32 v[156:157], v[210:211], v[156:157] op_sel_hi:[0,1]
	v_pk_fma_f32 v[156:157], v[82:83], v[156:157], v[86:87]
	v_pk_fma_f32 v[158:159], v[80:81], v[158:159], v[84:85]
	v_cndmask_b32_e64 v157, v157, v173, s[30:31]
	v_cndmask_b32_e64 v159, v159, v169, s[30:31]
	v_cndmask_b32_e64 v158, v158, v168, s[30:31]
	v_cndmask_b32_e64 v156, v156, v172, s[30:31]
	v_pk_fma_f32 v[232:233], v[156:157], s[70:71], v[154:155] op_sel_hi:[1,0,1]
	v_pk_fma_f32 v[154:155], v[158:159], s[70:71], v[152:153] op_sel_hi:[1,0,1]
	v_cvt_pk_bf16_f32 v152, v228, v229
	v_cvt_pk_bf16_f32 v153, v218, v219
	s_waitcnt vmcnt(6)
	s_nop 1
	v_mov_b32_e32 v160, v4
	v_mov_b32_e32 v161, v5
	v_mov_b32_e32 v162, v6
	v_mov_b32_e32 v163, v7
	v_lshlrev_b32_e32 v157, 16, v160
	v_add_f32_e32 v156, v154, v155
	v_mul_f32_e32 v205, v154, v154
	v_mul_f32_e32 v207, v155, v155
	v_cvt_pk_bf16_f32 v154, v154, v155
	v_cvt_pk_bf16_f32 v155, v232, v233
	global_store_dwordx4 v[216:217], v[152:155], off nt
	v_or_b32_e32 v216, 32, v188
	v_ashrrev_i32_e32 v217, 31, v216
	v_and_b32_e32 v159, 0xffff0000, v160
	v_lshlrev_b32_e32 v168, 16, v161
	v_and_b32_e32 v169, 0xffff0000, v161
	v_add_f32_e32 v198, v228, v229
	v_add_f32_e32 v200, v218, v219
	v_mul_f32_e32 v213, v228, v228
	v_mul_f32_e32 v215, v229, v229
	v_mul_f32_e32 v209, v218, v218
	v_mul_f32_e32 v211, v219, v219
	v_lshlrev_b64 v[228:229], 11, v[216:217]
	v_sub_f32_e32 v161, v169, v204
	v_sub_f32_e32 v160, v168, v204
	v_sub_f32_e32 v219, v159, v204
	v_sub_f32_e32 v218, v157, v204
	v_lshl_add_u64 v[234:235], v[190:191], 0, v[228:229]
	v_pk_mul_f32 v[218:219], v[206:207], v[218:219] op_sel_hi:[0,1]
	v_pk_mul_f32 v[160:161], v[206:207], v[160:161] op_sel_hi:[0,1]
	v_pk_fma_f32 v[160:161], v[90:91], v[160:161], v[94:95]
	v_pk_fma_f32 v[218:219], v[88:89], v[218:219], v[92:93]
	v_cndmask_b32_e64 v161, v161, v169, s[30:31]
	v_cndmask_b32_e64 v219, v219, v159, s[30:31]
	v_cndmask_b32_e64 v218, v218, v157, s[30:31]
	v_cndmask_b32_e64 v160, v160, v168, s[30:31]
	v_lshlrev_b32_e32 v168, 16, v163
	v_and_b32_e32 v169, 0xffff0000, v163
	v_pk_fma_f32 v[150:151], v[160:161], s[70:71], v[150:151] op_sel_hi:[1,0,1]
	v_pk_fma_f32 v[160:161], v[218:219], s[70:71], v[148:149] op_sel_hi:[1,0,1]
	v_lshlrev_b32_e32 v157, 16, v162
	v_and_b32_e32 v159, 0xffff0000, v162
	v_sub_f32_e32 v149, v169, v204
	v_sub_f32_e32 v148, v168, v204
	v_sub_f32_e32 v163, v159, v204
	v_sub_f32_e32 v162, v157, v204
	v_pk_mul_f32 v[148:149], v[206:207], v[148:149] op_sel_hi:[0,1]
	v_pk_mul_f32 v[162:163], v[206:207], v[162:163] op_sel_hi:[0,1]
	v_pk_fma_f32 v[148:149], v[82:83], v[148:149], v[86:87]
	v_pk_fma_f32 v[162:163], v[80:81], v[162:163], v[84:85]
	v_cndmask_b32_e64 v149, v149, v169, s[30:31]
	v_cndmask_b32_e64 v148, v148, v168, s[30:31]
	v_cndmask_b32_e64 v219, v163, v159, s[30:31]
	v_cndmask_b32_e64 v218, v162, v157, s[30:31]
	v_pk_fma_f32 v[162:163], v[148:149], s[70:71], v[146:147] op_sel_hi:[1,0,1]
	v_or_b32_e32 v148, 48, v188
	v_ashrrev_i32_e32 v149, 31, v148
	v_pk_fma_f32 v[218:219], v[218:219], s[70:71], v[144:145] op_sel_hi:[1,0,1]
	v_cvt_pk_bf16_f32 v144, v160, v161
	v_cvt_pk_bf16_f32 v145, v150, v151
	v_add_f32_e32 v158, v232, v233
	v_cvt_pk_bf16_f32 v146, v218, v219
	v_cvt_pk_bf16_f32 v147, v162, v163
	global_store_dwordx4 v[230:231], v[144:147], off nt
	v_lshlrev_b64 v[230:231], 11, v[148:149]
	v_mul_f32_e32 v197, v232, v232
	v_mul_f32_e32 v203, v233, v233
	v_lshl_add_u64 v[232:233], v[190:191], 0, v[230:231]
	s_waitcnt vmcnt(7)
	s_nop 1
	v_mov_b32_e32 v152, v8
	v_mov_b32_e32 v153, v9
	v_mov_b32_e32 v154, v10
	v_mov_b32_e32 v155, v11
	v_lshlrev_b32_e32 v157, 16, v152
	v_and_b32_e32 v159, 0xffff0000, v152
	v_lshlrev_b32_e32 v168, 16, v153
	v_and_b32_e32 v169, 0xffff0000, v153
	v_sub_f32_e32 v153, v169, v202
	v_sub_f32_e32 v152, v168, v202
	v_sub_f32_e32 v253, v159, v202
	v_sub_f32_e32 v252, v157, v202
	v_pk_mul_f32 v[252:253], v[178:179], v[252:253] op_sel_hi:[0,1]
	v_pk_mul_f32 v[152:153], v[178:179], v[152:153] op_sel_hi:[0,1]
	v_pk_fma_f32 v[152:153], v[90:91], v[152:153], v[94:95]
	v_pk_fma_f32 v[252:253], v[88:89], v[252:253], v[92:93]
	v_cndmask_b32_e64 v153, v153, v169, s[30:31]
	v_cndmask_b32_e64 v253, v253, v159, s[30:31]
	v_cndmask_b32_e64 v252, v252, v157, s[30:31]
	v_cndmask_b32_e64 v152, v152, v168, s[30:31]
	v_lshlrev_b32_e32 v157, 16, v154
	v_and_b32_e32 v159, 0xffff0000, v154
	v_lshlrev_b32_e32 v168, 16, v155
	v_and_b32_e32 v169, 0xffff0000, v155
	v_pk_fma_f32 v[142:143], v[152:153], s[70:71], v[142:143] op_sel_hi:[1,0,1]
	v_sub_f32_e32 v153, v169, v202
	v_sub_f32_e32 v152, v168, v202
	v_sub_f32_e32 v155, v159, v202
	v_sub_f32_e32 v154, v157, v202
	v_pk_mul_f32 v[154:155], v[178:179], v[154:155] op_sel_hi:[0,1]
	v_pk_mul_f32 v[152:153], v[178:179], v[152:153] op_sel_hi:[0,1]
	v_pk_fma_f32 v[152:153], v[82:83], v[152:153], v[86:87]
	v_pk_fma_f32 v[154:155], v[80:81], v[154:155], v[84:85]
	v_cndmask_b32_e64 v153, v153, v169, s[30:31]
	v_cndmask_b32_e64 v155, v155, v159, s[30:31]
	v_cndmask_b32_e64 v154, v154, v157, s[30:31]
	v_cndmask_b32_e64 v152, v152, v168, s[30:31]
	v_pk_fma_f32 v[140:141], v[252:253], s[70:71], v[140:141] op_sel_hi:[1,0,1]
	v_pk_fma_f32 v[138:139], v[152:153], s[70:71], v[138:139] op_sel_hi:[1,0,1]
	v_pk_fma_f32 v[136:137], v[154:155], s[70:71], v[136:137] op_sel_hi:[1,0,1]
	v_cvt_pk_bf16_f32 v152, v140, v141
	v_cvt_pk_bf16_f32 v153, v142, v143
	s_waitcnt vmcnt(6)
	s_nop 1
	v_mov_b32_e32 v144, v12
	v_mov_b32_e32 v145, v13
	v_mov_b32_e32 v146, v14
	v_mov_b32_e32 v147, v15
	v_lshlrev_b32_e32 v157, 16, v145
	v_cvt_pk_bf16_f32 v154, v136, v137
	v_cvt_pk_bf16_f32 v155, v138, v139
	global_store_dwordx4 v[234:235], v[152:155], off nt
	v_and_b32_e32 v159, 0xffff0000, v145
	v_sub_f32_e32 v145, v159, v196
	v_lshlrev_b32_e32 v154, 16, v144
	v_and_b32_e32 v155, 0xffff0000, v144
	v_sub_f32_e32 v144, v157, v196
	v_sub_f32_e32 v153, v155, v196
	v_sub_f32_e32 v152, v154, v196
	v_pk_mul_f32 v[152:153], v[176:177], v[152:153] op_sel_hi:[0,1]
	v_pk_mul_f32 v[144:145], v[176:177], v[144:145] op_sel_hi:[0,1]
	v_pk_fma_f32 v[144:145], v[90:91], v[144:145], v[94:95]
	v_pk_fma_f32 v[152:153], v[88:89], v[152:153], v[92:93]
	v_cndmask_b32_e64 v145, v145, v159, s[30:31]
	v_cndmask_b32_e64 v153, v153, v155, s[30:31]
	v_cndmask_b32_e64 v152, v152, v154, s[30:31]
	v_cndmask_b32_e64 v144, v144, v157, s[30:31]
	v_pk_fma_f32 v[134:135], v[144:145], s[70:71], v[134:135] op_sel_hi:[1,0,1]
	v_pk_fma_f32 v[144:145], v[152:153], s[70:71], v[132:133] op_sel_hi:[1,0,1]
	v_lshlrev_b32_e32 v152, 16, v146
	v_and_b32_e32 v153, 0xffff0000, v146
	v_lshlrev_b32_e32 v154, 16, v147
	v_and_b32_e32 v155, 0xffff0000, v147
	v_sub_f32_e32 v133, v155, v196
	v_sub_f32_e32 v132, v154, v196
	v_sub_f32_e32 v147, v153, v196
	v_sub_f32_e32 v146, v152, v196
	v_pk_mul_f32 v[146:147], v[176:177], v[146:147] op_sel_hi:[0,1]
	v_pk_mul_f32 v[132:133], v[176:177], v[132:133] op_sel_hi:[0,1]
	v_pk_fma_f32 v[132:133], v[82:83], v[132:133], v[86:87]
	v_pk_fma_f32 v[146:147], v[80:81], v[146:147], v[84:85]
	v_cndmask_b32_e64 v133, v133, v155, s[30:31]
	v_cndmask_b32_e64 v153, v147, v153, s[30:31]
	v_cndmask_b32_e64 v152, v146, v152, s[30:31]
	v_cndmask_b32_e64 v132, v132, v154, s[30:31]
	v_pk_fma_f32 v[146:147], v[132:133], s[70:71], v[130:131] op_sel_hi:[1,0,1]
	v_pk_fma_f32 v[152:153], v[152:153], s[70:71], v[128:129] op_sel_hi:[1,0,1]
	v_cvt_pk_bf16_f32 v128, v144, v145
	v_cvt_pk_bf16_f32 v129, v134, v135
	v_lshlrev_b64 v[132:133], 1, v[222:223]
	v_cvt_pk_bf16_f32 v130, v152, v153
	v_cvt_pk_bf16_f32 v131, v146, v147
	global_store_dwordx4 v[232:233], v[128:131], off nt
	v_lshl_add_u64 v[220:221], v[220:221], 0, v[132:133]
	v_lshl_add_u64 v[128:129], s[54:55], 0, v[224:225]
	v_lshl_add_u64 v[226:227], v[128:129], 0, v[132:133]
	s_waitcnt vmcnt(7)
	s_nop 1
	v_mov_b32_e32 v232, v16
	v_mov_b32_e32 v233, v17
	v_mov_b32_e32 v234, v18
	v_mov_b32_e32 v235, v19
	v_lshlrev_b32_e32 v157, 16, v232
	v_and_b32_e32 v159, 0xffff0000, v232
	v_lshlrev_b32_e32 v168, 16, v233
	v_and_b32_e32 v169, 0xffff0000, v233
	v_sub_f32_e32 v155, v169, v208
	v_sub_f32_e32 v154, v168, v208
	v_sub_f32_e32 v223, v159, v208
	v_sub_f32_e32 v222, v157, v208
	v_pk_mul_f32 v[222:223], v[210:211], v[222:223] op_sel_hi:[0,1]
	v_pk_mul_f32 v[154:155], v[210:211], v[154:155] op_sel_hi:[0,1]
	v_pk_fma_f32 v[154:155], v[74:75], v[154:155], v[78:79]
	v_pk_fma_f32 v[222:223], v[72:73], v[222:223], v[76:77]
	v_cndmask_b32_e64 v155, v155, v169, s[30:31]
	v_cndmask_b32_e64 v223, v223, v159, s[30:31]
	v_cndmask_b32_e64 v222, v222, v157, s[30:31]
	v_cndmask_b32_e64 v154, v154, v168, s[30:31]
	v_lshlrev_b32_e32 v157, 16, v234
	v_and_b32_e32 v159, 0xffff0000, v234
	v_lshlrev_b32_e32 v168, 16, v235
	v_and_b32_e32 v169, 0xffff0000, v235
	v_pk_fma_f32 v[126:127], v[154:155], s[70:71], v[126:127] op_sel_hi:[1,0,1]
	v_pk_fma_f32 v[154:155], v[222:223], s[70:71], v[124:125] op_sel_hi:[1,0,1]
	v_sub_f32_e32 v125, v169, v208
	v_sub_f32_e32 v124, v168, v208
	v_sub_f32_e32 v223, v159, v208
	v_sub_f32_e32 v222, v157, v208
	v_pk_mul_f32 v[222:223], v[210:211], v[222:223] op_sel_hi:[0,1]
	v_pk_mul_f32 v[124:125], v[210:211], v[124:125] op_sel_hi:[0,1]
	v_pk_fma_f32 v[124:125], v[66:67], v[124:125], v[70:71]
	v_pk_fma_f32 v[222:223], v[64:65], v[222:223], v[68:69]
	v_cndmask_b32_e64 v125, v125, v169, s[30:31]
	v_cndmask_b32_e64 v225, v223, v159, s[30:31]
	v_cndmask_b32_e64 v224, v222, v157, s[30:31]
	v_cndmask_b32_e64 v124, v124, v168, s[30:31]
	v_pk_fma_f32 v[222:223], v[124:125], s[70:71], v[122:123] op_sel_hi:[1,0,1]
	v_pk_fma_f32 v[224:225], v[224:225], s[70:71], v[120:121] op_sel_hi:[1,0,1]
	v_pk_mul_f32 v[120:121], v[222:223], v[222:223]
	v_pk_mul_f32 v[122:123], v[224:225], v[224:225]
	s_waitcnt vmcnt(6)
	s_nop 1
	v_mov_b32_e32 v128, v20
	v_mov_b32_e32 v129, v21
	v_mov_b32_e32 v130, v22
	v_mov_b32_e32 v131, v23
	v_and_b32_e32 v168, 0xffff0000, v128
	v_pk_mov_b32 v[124:125], v[122:123], v[120:121] op_sel:[1,0]
	v_mov_b32_e32 v123, v121
	v_pk_add_f32 v[120:121], v[124:125], v[122:123]
	v_lshlrev_b32_e32 v169, 16, v129
	v_pk_add_f32 v[124:125], v[120:121], v[120:121] op_sel_hi:[0,1]
	v_cvt_pk_bf16_f32 v120, v154, v155
	v_cvt_pk_bf16_f32 v121, v126, v127
	v_cvt_pk_bf16_f32 v122, v224, v225
	v_cvt_pk_bf16_f32 v123, v222, v223
	global_store_dwordx4 v[220:221], v[120:123], off nt
	v_lshlrev_b32_e32 v124, 16, v128
	v_and_b32_e32 v172, 0xffff0000, v129
	v_lshl_add_u64 v[120:121], s[54:55], 0, v[228:229]
	v_lshl_add_u64 v[220:221], v[120:121], 0, v[132:133]
	v_sub_f32_e32 v229, v168, v204
	v_sub_f32_e32 v228, v124, v204
	v_sub_f32_e32 v129, v172, v204
	v_sub_f32_e32 v128, v169, v204
	v_pk_mul_f32 v[228:229], v[206:207], v[228:229] op_sel_hi:[0,1]
	v_pk_mul_f32 v[128:129], v[206:207], v[128:129] op_sel_hi:[0,1]
	v_pk_fma_f32 v[228:229], v[72:73], v[228:229], v[76:77]
	v_pk_fma_f32 v[128:129], v[74:75], v[128:129], v[78:79]
	v_cndmask_b32_e64 v229, v229, v168, s[30:31]
	v_cndmask_b32_e64 v228, v228, v124, s[30:31]
	v_lshlrev_b32_e32 v124, 16, v130
	v_and_b32_e32 v168, 0xffff0000, v130
	v_cndmask_b32_e64 v129, v129, v172, s[30:31]
	v_cndmask_b32_e64 v128, v128, v169, s[30:31]
	v_lshlrev_b32_e32 v169, 16, v131
	v_and_b32_e32 v172, 0xffff0000, v131
	v_sub_f32_e32 v131, v168, v204
	v_sub_f32_e32 v130, v124, v204
	v_pk_fma_f32 v[118:119], v[128:129], s[70:71], v[118:119] op_sel_hi:[1,0,1]
	v_sub_f32_e32 v129, v172, v204
	v_sub_f32_e32 v128, v169, v204
	v_pk_mul_f32 v[130:131], v[206:207], v[130:131] op_sel_hi:[0,1]
	v_pk_mul_f32 v[128:129], v[206:207], v[128:129] op_sel_hi:[0,1]
	v_pk_fma_f32 v[130:131], v[64:65], v[130:131], v[68:69]
	v_pk_fma_f32 v[128:129], v[66:67], v[128:129], v[70:71]
	v_cndmask_b32_e64 v131, v131, v168, s[30:31]
	v_cndmask_b32_e64 v130, v130, v124, s[30:31]
	v_pk_fma_f32 v[116:117], v[228:229], s[70:71], v[116:117] op_sel_hi:[1,0,1]
	v_cndmask_b32_e64 v129, v129, v172, s[30:31]
	v_cndmask_b32_e64 v128, v128, v169, s[30:31]
	v_pk_fma_f32 v[130:131], v[130:131], s[70:71], v[112:113] op_sel_hi:[1,0,1]
	v_cvt_pk_bf16_f32 v112, v116, v117
	v_cvt_pk_bf16_f32 v113, v118, v119
	v_pk_fma_f32 v[128:129], v[128:129], s[70:71], v[114:115] op_sel_hi:[1,0,1]
	v_cvt_pk_bf16_f32 v114, v130, v131
	v_mov_b32_e32 v212, v154
	v_cvt_pk_bf16_f32 v115, v128, v129
	global_store_dwordx4 v[226:227], v[112:115], off nt
	v_mov_b32_e32 v214, v155
	v_mov_b32_e32 v208, v126
	v_lshl_add_u64 v[112:113], s[54:55], 0, v[230:231]
	v_lshl_add_u64 v[226:227], v[112:113], 0, v[132:133]
	v_mov_b32_e32 v210, v127
	v_mov_b32_e32 v204, v224
	v_mov_b32_e32 v206, v225
	v_mul_f32_e32 v199, v154, v154
	v_mul_f32_e32 v201, v155, v155
	v_mul_f32_e32 v157, v126, v126
	v_mul_f32_e32 v159, v127, v127
	s_waitcnt vmcnt(7)
	s_nop 1
	v_mov_b32_e32 v120, v24
	v_mov_b32_e32 v121, v25
	v_mov_b32_e32 v122, v26
	v_mov_b32_e32 v123, v27
	v_lshlrev_b32_e32 v124, 16, v120
	v_and_b32_e32 v168, 0xffff0000, v120
	v_lshlrev_b32_e32 v169, 16, v121
	v_and_b32_e32 v172, 0xffff0000, v121
	v_sub_f32_e32 v121, v172, v202
	v_sub_f32_e32 v120, v169, v202
	v_sub_f32_e32 v229, v168, v202
	v_sub_f32_e32 v228, v124, v202
	v_pk_mul_f32 v[228:229], v[178:179], v[228:229] op_sel_hi:[0,1]
	v_pk_mul_f32 v[120:121], v[178:179], v[120:121] op_sel_hi:[0,1]
	v_pk_fma_f32 v[120:121], v[74:75], v[120:121], v[78:79]
	v_pk_fma_f32 v[228:229], v[72:73], v[228:229], v[76:77]
	v_cndmask_b32_e64 v121, v121, v172, s[30:31]
	v_cndmask_b32_e64 v229, v229, v168, s[30:31]
	v_cndmask_b32_e64 v228, v228, v124, s[30:31]
	v_cndmask_b32_e64 v120, v120, v169, s[30:31]
	v_lshlrev_b32_e32 v124, 16, v122
	v_and_b32_e32 v168, 0xffff0000, v122
	v_lshlrev_b32_e32 v169, 16, v123
	v_and_b32_e32 v172, 0xffff0000, v123
	v_pk_fma_f32 v[110:111], v[120:121], s[70:71], v[110:111] op_sel_hi:[1,0,1]
	v_sub_f32_e32 v121, v172, v202
	v_sub_f32_e32 v120, v169, v202
	v_sub_f32_e32 v123, v168, v202
	v_sub_f32_e32 v122, v124, v202
	v_pk_mul_f32 v[122:123], v[178:179], v[122:123] op_sel_hi:[0,1]
	v_pk_mul_f32 v[120:121], v[178:179], v[120:121] op_sel_hi:[0,1]
	v_pk_fma_f32 v[120:121], v[66:67], v[120:121], v[70:71]
	v_pk_fma_f32 v[122:123], v[64:65], v[122:123], v[68:69]
	v_cndmask_b32_e64 v121, v121, v172, s[30:31]
	v_cndmask_b32_e64 v123, v123, v168, s[30:31]
	v_cndmask_b32_e64 v122, v122, v124, s[30:31]
	v_cndmask_b32_e64 v120, v120, v169, s[30:31]
	v_pk_fma_f32 v[108:109], v[228:229], s[70:71], v[108:109] op_sel_hi:[1,0,1]
	v_pk_fma_f32 v[106:107], v[120:121], s[70:71], v[106:107] op_sel_hi:[1,0,1]
	v_pk_fma_f32 v[104:105], v[122:123], s[70:71], v[104:105] op_sel_hi:[1,0,1]
	v_cvt_pk_bf16_f32 v120, v108, v109
	v_cvt_pk_bf16_f32 v121, v110, v111
	v_mov_b32_e32 v202, v223
	v_cvt_pk_bf16_f32 v122, v104, v105
	v_cvt_pk_bf16_f32 v123, v106, v107
	global_store_dwordx4 v[220:221], v[120:123], off nt
	s_waitcnt vmcnt(7)
	s_nop 1
	v_mov_b32_e32 v112, v28
	v_mov_b32_e32 v113, v29
	v_mov_b32_e32 v114, v30
	v_mov_b32_e32 v115, v31
	v_lshlrev_b32_e32 v124, 16, v113
	v_and_b32_e32 v168, 0xffff0000, v113
	v_lshlrev_b32_e32 v122, 16, v112
	v_and_b32_e32 v123, 0xffff0000, v112
	v_sub_f32_e32 v113, v168, v196
	v_sub_f32_e32 v112, v124, v196
	v_sub_f32_e32 v121, v123, v196
	v_sub_f32_e32 v120, v122, v196
	v_pk_mul_f32 v[120:121], v[176:177], v[120:121] op_sel_hi:[0,1]
	v_pk_mul_f32 v[112:113], v[176:177], v[112:113] op_sel_hi:[0,1]
	v_pk_fma_f32 v[112:113], v[74:75], v[112:113], v[78:79]
	v_pk_fma_f32 v[120:121], v[72:73], v[120:121], v[76:77]
	v_cndmask_b32_e64 v113, v113, v168, s[30:31]
	v_cndmask_b32_e64 v121, v121, v123, s[30:31]
	v_cndmask_b32_e64 v120, v120, v122, s[30:31]
	v_cndmask_b32_e64 v112, v112, v124, s[30:31]
	v_lshlrev_b32_e32 v122, 16, v115
	v_and_b32_e32 v123, 0xffff0000, v115
	v_pk_fma_f32 v[102:103], v[112:113], s[70:71], v[102:103] op_sel_hi:[1,0,1]
	v_pk_fma_f32 v[100:101], v[120:121], s[70:71], v[100:101] op_sel_hi:[1,0,1]
	v_lshlrev_b32_e32 v120, 16, v114
	v_and_b32_e32 v121, 0xffff0000, v114
	v_sub_f32_e32 v113, v123, v196
	v_sub_f32_e32 v112, v122, v196
	v_sub_f32_e32 v115, v121, v196
	v_sub_f32_e32 v114, v120, v196
	v_pk_mul_f32 v[112:113], v[176:177], v[112:113] op_sel_hi:[0,1]
	v_pk_mul_f32 v[114:115], v[176:177], v[114:115] op_sel_hi:[0,1]
	v_pk_fma_f32 v[112:113], v[66:67], v[112:113], v[70:71]
	v_pk_fma_f32 v[114:115], v[64:65], v[114:115], v[68:69]
	v_cndmask_b32_e64 v113, v113, v123, s[30:31]
	v_cndmask_b32_e64 v112, v112, v122, s[30:31]
	v_cndmask_b32_e64 v115, v115, v121, s[30:31]
	v_cndmask_b32_e64 v114, v114, v120, s[30:31]
	v_pk_fma_f32 v[98:99], v[112:113], s[70:71], v[98:99] op_sel_hi:[1,0,1]
	v_cvt_pk_bf16_f32 v112, v100, v101
	v_cvt_pk_bf16_f32 v113, v102, v103
	v_pk_fma_f32 v[96:97], v[114:115], s[70:71], v[96:97] op_sel_hi:[1,0,1]
	v_mov_b32_e32 v196, v222
	v_cvt_pk_bf16_f32 v114, v96, v97
	v_cvt_pk_bf16_f32 v115, v98, v99
	global_store_dwordx4 v[226:227], v[112:115], off nt
	v_pk_add_f32 v[120:121], v[196:197], v[202:203]
	v_mov_b32_e32 v124, v175
	v_and_b32_e32 v113, 64, v237
	v_xor_b32_e32 v112, 16, v237
	v_add_u32_e32 v113, 64, v113
	v_cmp_lt_i32_e32 vcc, v112, v113
	v_pk_add_f32 v[114:115], v[208:209], v[210:211]
	s_nop 0
	v_cndmask_b32_e32 v112, v237, v112, vcc
	v_lshlrev_b32_e32 v178, 2, v112
	v_xor_b32_e32 v112, 32, v237
	v_cmp_lt_i32_e32 vcc, v112, v113
	s_nop 1
	v_cndmask_b32_e32 v112, v237, v112, vcc
	v_lshlrev_b32_e32 v176, 2, v112
	v_pk_add_f32 v[112:113], v[212:213], v[214:215]
	s_nop 0
	v_pk_add_f32 v[112:113], v[112:113], v[114:115]
	v_pk_add_f32 v[114:115], v[204:205], v[206:207]
	s_nop 0
	v_pk_add_f32 v[114:115], v[114:115], v[120:121]
	v_pk_add_f32 v[120:121], v[156:157], v[158:159]
	v_pk_add_f32 v[112:113], v[112:113], v[114:115]
	v_pk_add_f32 v[114:115], v[198:199], v[200:201]
	s_nop 0
	v_pk_add_f32 v[114:115], v[114:115], v[120:121]
	s_nop 0
	v_pk_add_f32 v[114:115], v[114:115], v[124:125]
	s_nop 0
	v_pk_add_f32 v[112:113], v[112:113], v[114:115]
	ds_bpermute_b32 v114, v178, v112
	ds_bpermute_b32 v115, v178, v113
	s_waitcnt lgkmcnt(0)
	v_pk_add_f32 v[112:113], v[112:113], v[114:115]
	ds_bpermute_b32 v114, v176, v112
	ds_bpermute_b32 v115, v176, v113
	s_and_saveexec_b64 s[10:11], s[26:27]
	s_cbranch_execz .LBB0_1065
	v_lshlrev_b64 v[120:121], 7, v[188:189]
	v_lshl_add_u64 v[120:121], s[50:51], 0, v[120:121]
	s_waitcnt lgkmcnt(0)
	v_pk_add_f32 v[112:113], v[112:113], v[114:115]
	global_store_dwordx2 v[120:121], v[112:113], off

.LBB0_1079:
	v_add_u32_e32 v102, 0x80, v188
	v_ashrrev_i32_e32 v103, 31, v102
	v_lshlrev_b64 v[126:127], 11, v[102:103]
	v_add_u32_e32 v96, 0x90, v188
	v_lshl_add_u64 v[120:121], s[54:55], 0, v[126:127]
	v_ashrrev_i32_e32 v97, 31, v96
	v_lshl_add_u64 v[122:123], v[192:193], 1, v[120:121]
	v_lshlrev_b64 v[124:125], 11, v[96:97]
	v_lshl_add_u32 v130, v237, 4, s58
	v_add_u32_e32 v131, 0x10000, v130
	ds_read_b128 v[0:3], v130 offset:49152
	ds_read_b128 v[4:7], v130 offset:57344
	ds_read_b128 v[8:11], v131
	ds_read_b128 v[12:15], v131 offset:8192
	ds_read_b128 v[16:19], v130
	ds_read_b128 v[20:23], v130 offset:8192
	ds_read_b128 v[24:27], v131 offset:16384
	ds_read_b128 v[28:31], v131 offset:24576
	s_mov_b32 s101, 0
	s_mov_b32 s100, 0x8000
	v_lshl_add_u64 v[98:99], v[122:123], 0, s[100:101]
	s_mov_b32 s100, 0x10000
	v_lshl_add_u64 v[100:101], v[122:123], 0, s[100:101]
	s_mov_b32 s100, 0x18000
	v_lshl_add_u64 v[128:129], v[122:123], 0, s[100:101]
	global_load_dwordx4 v[192:195], v[122:123], off
	global_load_dwordx4 v[196:199], v[98:99], off
	global_load_dwordx4 v[200:203], v[100:101], off
	global_load_dwordx4 v[204:207], v[128:129], off
	global_load_dwordx4 v[208:211], v[122:123], off offset:256
	global_load_dwordx4 v[212:215], v[98:99], off offset:256
	global_load_dwordx4 v[216:219], v[100:101], off offset:256
	global_load_dwordx4 v[220:223], v[128:129], off offset:256
	s_waitcnt lgkmcnt(0)
	v_lshl_add_u64 v[134:135], v[190:191], 0, v[124:125]
	v_add_u32_e32 v100, 0xa0, v188
	s_waitcnt lgkmcnt(1)
	v_add_u32_e32 v98, 0xb0, v188
	v_ashrrev_i32_e32 v101, 31, v100
	s_waitcnt lgkmcnt(0)
	v_ashrrev_i32_e32 v99, 31, v98
	v_lshlrev_b64 v[130:131], 11, v[100:101]
	v_lshlrev_b64 v[128:129], 11, v[98:99]
	v_lshl_add_u64 v[146:147], v[190:191], 0, v[126:127]
	v_lshl_add_u64 v[136:137], v[190:191], 0, v[130:131]
	v_lshl_add_u64 v[126:127], v[190:191], 0, v[128:129]
	v_lshl_add_u64 v[120:121], v[120:121], 0, v[132:133]
	s_waitcnt vmcnt(7)
	s_nop 1
	v_mov_b32_e32 v138, v192
	v_mov_b32_e32 v139, v193
	v_mov_b32_e32 v140, v194
	v_mov_b32_e32 v141, v195
	v_lshlrev_b32_e32 v105, 16, v138
	v_and_b32_e32 v107, 0xffff0000, v138
	v_lshlrev_b32_e32 v109, 16, v139
	v_and_b32_e32 v111, 0xffff0000, v139
	v_lshlrev_b32_e32 v113, 16, v140
	v_and_b32_e32 v115, 0xffff0000, v140
	v_lshlrev_b32_e32 v117, 16, v141
	v_and_b32_e32 v119, 0xffff0000, v141
	s_waitcnt vmcnt(6)
	s_nop 1
	v_mov_b32_e32 v142, v196
	v_mov_b32_e32 v143, v197
	v_mov_b32_e32 v144, v198
	v_mov_b32_e32 v145, v199
	v_lshlrev_b32_e32 v156, 16, v142
	v_and_b32_e32 v157, 0xffff0000, v142
	v_lshlrev_b32_e32 v158, 16, v143
	v_and_b32_e32 v159, 0xffff0000, v143
	v_lshlrev_b32_e32 v160, 16, v144
	v_and_b32_e32 v161, 0xffff0000, v144
	v_lshlrev_b32_e32 v162, 16, v145
	v_and_b32_e32 v163, 0xffff0000, v145
	v_sub_f32_e32 v139, v111, v118
	v_sub_f32_e32 v138, v109, v118
	v_sub_f32_e32 v141, v107, v118
	v_sub_f32_e32 v140, v105, v118
	v_sub_f32_e32 v143, v119, v118
	v_sub_f32_e32 v142, v117, v118
	v_sub_f32_e32 v145, v115, v118
	v_sub_f32_e32 v144, v113, v118
	v_sub_f32_e32 v149, v159, v114
	v_sub_f32_e32 v148, v158, v114
	v_sub_f32_e32 v151, v157, v114
	v_sub_f32_e32 v150, v156, v114
	v_sub_f32_e32 v153, v163, v114
	v_sub_f32_e32 v152, v162, v114
	v_sub_f32_e32 v155, v161, v114
	v_sub_f32_e32 v154, v160, v114
	v_pk_mul_f32 v[140:141], v[116:117], v[140:141] op_sel_hi:[0,1]
	v_pk_mul_f32 v[138:139], v[116:117], v[138:139] op_sel_hi:[0,1]
	v_pk_mul_f32 v[144:145], v[116:117], v[144:145] op_sel_hi:[0,1]
	v_pk_mul_f32 v[142:143], v[116:117], v[142:143] op_sel_hi:[0,1]
	v_pk_mul_f32 v[150:151], v[112:113], v[150:151] op_sel_hi:[0,1]
	v_pk_mul_f32 v[148:149], v[112:113], v[148:149] op_sel_hi:[0,1]
	v_pk_mul_f32 v[154:155], v[112:113], v[154:155] op_sel_hi:[0,1]
	v_pk_mul_f32 v[152:153], v[112:113], v[152:153] op_sel_hi:[0,1]
	v_pk_fma_f32 v[138:139], v[90:91], v[138:139], v[94:95]
	v_pk_fma_f32 v[140:141], v[88:89], v[140:141], v[92:93]
	v_pk_fma_f32 v[142:143], v[82:83], v[142:143], v[86:87]
	v_pk_fma_f32 v[144:145], v[80:81], v[144:145], v[84:85]
	v_pk_fma_f32 v[148:149], v[90:91], v[148:149], v[94:95]
	v_pk_fma_f32 v[150:151], v[88:89], v[150:151], v[92:93]
	v_pk_fma_f32 v[152:153], v[82:83], v[152:153], v[86:87]
	v_pk_fma_f32 v[154:155], v[80:81], v[154:155], v[84:85]
	v_cndmask_b32_e64 v141, v141, v107, s[30:31]
	v_cndmask_b32_e64 v140, v140, v105, s[30:31]
	v_cndmask_b32_e64 v139, v139, v111, s[30:31]
	v_cndmask_b32_e64 v138, v138, v109, s[30:31]
	v_cndmask_b32_e64 v145, v145, v115, s[30:31]
	v_cndmask_b32_e64 v144, v144, v113, s[30:31]
	v_cndmask_b32_e64 v143, v143, v119, s[30:31]
	v_cndmask_b32_e64 v142, v142, v117, s[30:31]
	v_cndmask_b32_e64 v151, v151, v157, s[30:31]
	v_cndmask_b32_e64 v150, v150, v156, s[30:31]
	v_pk_fma_f32 v[62:63], v[138:139], s[70:71], v[62:63] op_sel_hi:[1,0,1]
	v_pk_fma_f32 v[60:61], v[140:141], s[70:71], v[60:61] op_sel_hi:[1,0,1]
	v_pk_fma_f32 v[58:59], v[142:143], s[70:71], v[58:59] op_sel_hi:[1,0,1]
	v_pk_fma_f32 v[56:57], v[144:145], s[70:71], v[56:57] op_sel_hi:[1,0,1]
	v_cvt_pk_bf16_f32 v138, v60, v61
	v_cvt_pk_bf16_f32 v139, v62, v63
	v_cndmask_b32_e64 v149, v149, v159, s[30:31]
	v_cvt_pk_bf16_f32 v140, v56, v57
	v_cvt_pk_bf16_f32 v141, v58, v59
	v_cndmask_b32_e64 v148, v148, v158, s[30:31]
	v_cndmask_b32_e64 v155, v155, v161, s[30:31]
	v_cndmask_b32_e64 v154, v154, v160, s[30:31]
	v_cndmask_b32_e64 v153, v153, v163, s[30:31]
	v_cndmask_b32_e64 v152, v152, v162, s[30:31]
	v_pk_fma_f32 v[54:55], v[148:149], s[70:71], v[54:55] op_sel_hi:[1,0,1]
	v_pk_fma_f32 v[52:53], v[150:151], s[70:71], v[52:53] op_sel_hi:[1,0,1]
	v_pk_fma_f32 v[50:51], v[152:153], s[70:71], v[50:51] op_sel_hi:[1,0,1]
	v_pk_fma_f32 v[48:49], v[154:155], s[70:71], v[48:49] op_sel_hi:[1,0,1]
	global_store_dwordx4 v[146:147], v[138:141], off nt
	s_waitcnt vmcnt(6)
	s_nop 1
	v_mov_b32_e32 v142, v200
	v_mov_b32_e32 v143, v201
	v_mov_b32_e32 v144, v202
	v_mov_b32_e32 v145, v203
	v_lshlrev_b32_e32 v105, 16, v142
	v_cvt_pk_bf16_f32 v138, v52, v53
	v_cvt_pk_bf16_f32 v139, v54, v55
	v_cvt_pk_bf16_f32 v140, v48, v49
	v_cvt_pk_bf16_f32 v141, v50, v51
	v_and_b32_e32 v107, 0xffff0000, v142
	v_lshlrev_b32_e32 v109, 16, v143
	v_and_b32_e32 v111, 0xffff0000, v143
	v_lshlrev_b32_e32 v113, 16, v144
	v_and_b32_e32 v115, 0xffff0000, v144
	v_lshlrev_b32_e32 v117, 16, v145
	v_and_b32_e32 v119, 0xffff0000, v145
	global_store_dwordx4 v[134:135], v[138:141], off nt
	v_sub_f32_e32 v135, v111, v110
	v_sub_f32_e32 v134, v109, v110
	v_sub_f32_e32 v139, v107, v110
	v_sub_f32_e32 v138, v105, v110
	v_sub_f32_e32 v141, v119, v110
	v_sub_f32_e32 v140, v117, v110
	v_sub_f32_e32 v143, v115, v110
	v_sub_f32_e32 v142, v113, v110
	v_pk_mul_f32 v[138:139], v[108:109], v[138:139] op_sel_hi:[0,1]
	v_pk_mul_f32 v[134:135], v[108:109], v[134:135] op_sel_hi:[0,1]
	v_pk_mul_f32 v[142:143], v[108:109], v[142:143] op_sel_hi:[0,1]
	v_pk_mul_f32 v[140:141], v[108:109], v[140:141] op_sel_hi:[0,1]
	v_pk_fma_f32 v[134:135], v[90:91], v[134:135], v[94:95]
	v_pk_fma_f32 v[138:139], v[88:89], v[138:139], v[92:93]
	v_pk_fma_f32 v[140:141], v[82:83], v[140:141], v[86:87]
	v_pk_fma_f32 v[142:143], v[80:81], v[142:143], v[84:85]
	v_cndmask_b32_e64 v139, v139, v107, s[30:31]
	v_cndmask_b32_e64 v138, v138, v105, s[30:31]
	v_cndmask_b32_e64 v135, v135, v111, s[30:31]
	v_cndmask_b32_e64 v134, v134, v109, s[30:31]
	v_cndmask_b32_e64 v143, v143, v115, s[30:31]
	v_cndmask_b32_e64 v142, v142, v113, s[30:31]
	v_cndmask_b32_e64 v141, v141, v119, s[30:31]
	v_cndmask_b32_e64 v140, v140, v117, s[30:31]
	v_pk_fma_f32 v[46:47], v[134:135], s[70:71], v[46:47] op_sel_hi:[1,0,1]
	v_pk_fma_f32 v[44:45], v[138:139], s[70:71], v[44:45] op_sel_hi:[1,0,1]
	v_pk_fma_f32 v[42:43], v[140:141], s[70:71], v[42:43] op_sel_hi:[1,0,1]
	v_pk_fma_f32 v[40:41], v[142:143], s[70:71], v[40:41] op_sel_hi:[1,0,1]
	s_waitcnt vmcnt(6)
	s_nop 1
	v_mov_b32_e32 v146, v204
	v_mov_b32_e32 v147, v205
	v_mov_b32_e32 v148, v206
	v_mov_b32_e32 v149, v207
	v_lshlrev_b32_e32 v152, 16, v146
	v_and_b32_e32 v153, 0xffff0000, v146
	v_lshlrev_b32_e32 v154, 16, v147
	v_and_b32_e32 v155, 0xffff0000, v147
	v_lshlrev_b32_e32 v156, 16, v148
	v_and_b32_e32 v157, 0xffff0000, v148
	v_lshlrev_b32_e32 v158, 16, v149
	v_and_b32_e32 v159, 0xffff0000, v149
	v_sub_f32_e32 v145, v155, v106
	v_sub_f32_e32 v144, v154, v106
	v_sub_f32_e32 v147, v153, v106
	v_sub_f32_e32 v146, v152, v106
	v_sub_f32_e32 v149, v159, v106
	v_sub_f32_e32 v148, v158, v106
	v_sub_f32_e32 v151, v157, v106
	v_sub_f32_e32 v150, v156, v106
	v_pk_mul_f32 v[146:147], v[104:105], v[146:147] op_sel_hi:[0,1]
	v_pk_mul_f32 v[144:145], v[104:105], v[144:145] op_sel_hi:[0,1]
	v_pk_mul_f32 v[150:151], v[104:105], v[150:151] op_sel_hi:[0,1]
	v_pk_mul_f32 v[148:149], v[104:105], v[148:149] op_sel_hi:[0,1]
	v_pk_fma_f32 v[90:91], v[90:91], v[144:145], v[94:95]
	v_pk_fma_f32 v[88:89], v[88:89], v[146:147], v[92:93]
	v_pk_fma_f32 v[82:83], v[82:83], v[148:149], v[86:87]
	v_pk_fma_f32 v[80:81], v[80:81], v[150:151], v[84:85]
	v_cndmask_b32_e64 v85, v89, v153, s[30:31]
	v_cndmask_b32_e64 v84, v88, v152, s[30:31]
	v_cndmask_b32_e64 v87, v91, v155, s[30:31]
	v_cndmask_b32_e64 v86, v90, v154, s[30:31]
	v_cndmask_b32_e64 v89, v81, v157, s[30:31]
	v_cndmask_b32_e64 v88, v80, v156, s[30:31]
	v_cndmask_b32_e64 v91, v83, v159, s[30:31]
	v_cndmask_b32_e64 v90, v82, v158, s[30:31]
	v_cvt_pk_bf16_f32 v80, v44, v45
	v_cvt_pk_bf16_f32 v81, v46, v47
	v_cvt_pk_bf16_f32 v82, v40, v41
	v_cvt_pk_bf16_f32 v83, v42, v43
	v_pk_fma_f32 v[38:39], v[86:87], s[70:71], v[38:39] op_sel_hi:[1,0,1]
	v_pk_fma_f32 v[36:37], v[84:85], s[70:71], v[36:37] op_sel_hi:[1,0,1]
	global_store_dwordx4 v[136:137], v[80:83], off nt
	v_pk_fma_f32 v[34:35], v[90:91], s[70:71], v[34:35] op_sel_hi:[1,0,1]
	v_pk_fma_f32 v[32:33], v[88:89], s[70:71], v[32:33] op_sel_hi:[1,0,1]
	v_cvt_pk_bf16_f32 v84, v36, v37
	v_cvt_pk_bf16_f32 v85, v38, v39
	v_lshl_add_u64 v[80:81], s[54:55], 0, v[124:125]
	v_cvt_pk_bf16_f32 v86, v32, v33
	v_cvt_pk_bf16_f32 v87, v34, v35
	v_lshl_add_u64 v[82:83], v[80:81], 0, v[132:133]
	v_lshl_add_u64 v[80:81], s[54:55], 0, v[130:131]
	v_lshl_add_u64 v[122:123], s[54:55], 0, v[128:129]
	v_lshl_add_u64 v[124:125], v[80:81], 0, v[132:133]
	v_lshl_add_u64 v[80:81], v[122:123], 0, v[132:133]
	global_store_dwordx4 v[126:127], v[84:87], off nt
	s_waitcnt vmcnt(7)
	s_nop 1
	v_mov_b32_e32 v88, v208
	v_mov_b32_e32 v89, v209
	v_mov_b32_e32 v90, v210
	v_mov_b32_e32 v91, v211
	v_lshlrev_b32_e32 v105, 16, v88
	v_and_b32_e32 v107, 0xffff0000, v88
	v_lshlrev_b32_e32 v109, 16, v89
	v_and_b32_e32 v111, 0xffff0000, v89
	v_lshlrev_b32_e32 v117, 16, v90
	v_and_b32_e32 v122, 0xffff0000, v90
	v_lshlrev_b32_e32 v123, 16, v91
	v_and_b32_e32 v126, 0xffff0000, v91
	v_sub_f32_e32 v85, v111, v118
	v_sub_f32_e32 v84, v109, v118
	v_sub_f32_e32 v87, v107, v118
	v_sub_f32_e32 v86, v105, v118
	v_sub_f32_e32 v89, v126, v118
	v_sub_f32_e32 v88, v123, v118
	v_sub_f32_e32 v91, v122, v118
	v_sub_f32_e32 v90, v117, v118
	v_pk_mul_f32 v[86:87], v[116:117], v[86:87] op_sel_hi:[0,1]
	v_pk_mul_f32 v[84:85], v[116:117], v[84:85] op_sel_hi:[0,1]
	v_pk_mul_f32 v[90:91], v[116:117], v[90:91] op_sel_hi:[0,1]
	v_pk_mul_f32 v[88:89], v[116:117], v[88:89] op_sel_hi:[0,1]
	s_waitcnt vmcnt(6)
	s_nop 1
	v_mov_b32_e32 v92, v212
	v_mov_b32_e32 v93, v213
	v_mov_b32_e32 v94, v214
	v_mov_b32_e32 v95, v215
	v_lshlrev_b32_e32 v127, 16, v92
	v_and_b32_e32 v128, 0xffff0000, v92
	v_lshlrev_b32_e32 v129, 16, v93
	v_and_b32_e32 v130, 0xffff0000, v93
	v_lshlrev_b32_e32 v131, 16, v94
	v_and_b32_e32 v132, 0xffff0000, v94
	v_lshlrev_b32_e32 v133, 16, v95
	v_and_b32_e32 v134, 0xffff0000, v95
	v_pk_fma_f32 v[84:85], v[74:75], v[84:85], v[78:79]
	v_pk_fma_f32 v[86:87], v[72:73], v[86:87], v[76:77]
	v_pk_fma_f32 v[88:89], v[66:67], v[88:89], v[70:71]
	v_pk_fma_f32 v[90:91], v[64:65], v[90:91], v[68:69]
	v_sub_f32_e32 v93, v130, v114
	v_sub_f32_e32 v92, v129, v114
	v_sub_f32_e32 v95, v128, v114
	v_sub_f32_e32 v94, v127, v114
	v_sub_f32_e32 v119, v134, v114
	v_sub_f32_e32 v118, v133, v114
	v_sub_f32_e32 v115, v132, v114
	v_sub_f32_e32 v114, v131, v114
	v_cndmask_b32_e64 v87, v87, v107, s[30:31]
	v_cndmask_b32_e64 v86, v86, v105, s[30:31]
	v_cndmask_b32_e64 v85, v85, v111, s[30:31]
	v_cndmask_b32_e64 v84, v84, v109, s[30:31]
	v_cndmask_b32_e64 v91, v91, v122, s[30:31]
	v_cndmask_b32_e64 v90, v90, v117, s[30:31]
	v_cndmask_b32_e64 v89, v89, v126, s[30:31]
	v_cndmask_b32_e64 v88, v88, v123, s[30:31]
	v_pk_mul_f32 v[94:95], v[112:113], v[94:95] op_sel_hi:[0,1]
	v_pk_mul_f32 v[92:93], v[112:113], v[92:93] op_sel_hi:[0,1]
	v_pk_mul_f32 v[114:115], v[112:113], v[114:115] op_sel_hi:[0,1]
	v_pk_mul_f32 v[112:113], v[112:113], v[118:119] op_sel_hi:[0,1]
	v_pk_fma_f32 v[116:117], v[84:85], s[70:71], v[30:31] op_sel_hi:[1,0,1]
	v_pk_fma_f32 v[118:119], v[86:87], s[70:71], v[28:29] op_sel_hi:[1,0,1]
	v_pk_fma_f32 v[88:89], v[88:89], s[70:71], v[26:27] op_sel_hi:[1,0,1]
	v_pk_fma_f32 v[90:91], v[90:91], s[70:71], v[24:25] op_sel_hi:[1,0,1]
	v_cvt_pk_bf16_f32 v24, v118, v119
	v_cvt_pk_bf16_f32 v25, v116, v117
	v_pk_fma_f32 v[92:93], v[74:75], v[92:93], v[78:79]
	v_cvt_pk_bf16_f32 v26, v90, v91
	v_cvt_pk_bf16_f32 v27, v88, v89
	v_pk_fma_f32 v[94:95], v[72:73], v[94:95], v[76:77]
	v_pk_fma_f32 v[112:113], v[66:67], v[112:113], v[70:71]
	v_pk_fma_f32 v[114:115], v[64:65], v[114:115], v[68:69]
	v_cndmask_b32_e64 v95, v95, v128, s[30:31]
	v_cndmask_b32_e64 v94, v94, v127, s[30:31]
	v_cndmask_b32_e64 v85, v93, v130, s[30:31]
	v_cndmask_b32_e64 v84, v92, v129, s[30:31]
	v_cndmask_b32_e64 v87, v115, v132, s[30:31]
	v_cndmask_b32_e64 v86, v114, v131, s[30:31]
	v_cndmask_b32_e64 v93, v113, v134, s[30:31]
	v_cndmask_b32_e64 v92, v112, v133, s[30:31]
	v_pk_fma_f32 v[22:23], v[84:85], s[70:71], v[22:23] op_sel_hi:[1,0,1]
	v_pk_fma_f32 v[20:21], v[94:95], s[70:71], v[20:21] op_sel_hi:[1,0,1]
	v_pk_fma_f32 v[18:19], v[92:93], s[70:71], v[18:19] op_sel_hi:[1,0,1]
	v_pk_fma_f32 v[16:17], v[86:87], s[70:71], v[16:17] op_sel_hi:[1,0,1]
	global_store_dwordx4 v[120:121], v[24:27], off nt
	v_pk_mul_f32 v[120:121], v[88:89], v[88:89]
	v_pk_mul_f32 v[122:123], v[90:91], v[90:91]
	v_cvt_pk_bf16_f32 v24, v20, v21
	v_cvt_pk_bf16_f32 v25, v22, v23
	v_cvt_pk_bf16_f32 v26, v16, v17
	v_cvt_pk_bf16_f32 v27, v18, v19
	v_pk_mov_b32 v[126:127], v[122:123], v[120:121] op_sel:[1,0]
	v_mov_b32_e32 v123, v121
	v_pk_add_f32 v[120:121], v[126:127], v[122:123]
	global_store_dwordx4 v[82:83], v[24:27], off nt
	v_pk_add_f32 v[82:83], v[120:121], v[120:121] op_sel_hi:[0,1]
	v_add_f32_e32 v92, v60, v61
	v_add_f32_e32 v94, v62, v63
	v_add_f32_e32 v112, v56, v57
	v_add_f32_e32 v114, v58, v59
	v_mul_f32_e32 v105, v60, v60
	v_mul_f32_e32 v107, v62, v62
	v_mul_f32_e32 v109, v56, v56
	v_mul_f32_e32 v111, v58, v58
	v_mul_f32_e32 v61, v61, v61
	v_mul_f32_e32 v63, v63, v63
	v_mul_f32_e32 v57, v57, v57
	v_mul_f32_e32 v59, v59, v59
	v_mul_f32_e32 v93, v118, v118
	v_mul_f32_e32 v95, v119, v119
	v_mul_f32_e32 v113, v116, v116
	v_mul_f32_e32 v115, v117, v117
	s_waitcnt vmcnt(7)
	s_nop 1
	v_mov_b32_e32 v28, v216
	v_mov_b32_e32 v29, v217
	v_mov_b32_e32 v30, v218
	v_mov_b32_e32 v31, v219
	v_lshlrev_b32_e32 v56, 16, v28
	v_and_b32_e32 v58, 0xffff0000, v28
	v_lshlrev_b32_e32 v60, 16, v29
	v_and_b32_e32 v62, 0xffff0000, v29
	v_lshlrev_b32_e32 v82, 16, v30
	v_and_b32_e32 v122, 0xffff0000, v30
	v_lshlrev_b32_e32 v123, 16, v31
	v_and_b32_e32 v126, 0xffff0000, v31
	v_sub_f32_e32 v25, v62, v110
	v_sub_f32_e32 v24, v60, v110
	v_sub_f32_e32 v27, v58, v110
	v_sub_f32_e32 v26, v56, v110
	v_sub_f32_e32 v29, v126, v110
	v_sub_f32_e32 v28, v123, v110
	v_sub_f32_e32 v31, v122, v110
	v_sub_f32_e32 v30, v82, v110
	v_pk_mul_f32 v[26:27], v[108:109], v[26:27] op_sel_hi:[0,1]
	v_pk_mul_f32 v[24:25], v[108:109], v[24:25] op_sel_hi:[0,1]
	v_pk_mul_f32 v[30:31], v[108:109], v[30:31] op_sel_hi:[0,1]
	v_pk_mul_f32 v[28:29], v[108:109], v[28:29] op_sel_hi:[0,1]
	v_pk_fma_f32 v[24:25], v[74:75], v[24:25], v[78:79]
	v_pk_fma_f32 v[26:27], v[72:73], v[26:27], v[76:77]
	v_pk_fma_f32 v[28:29], v[66:67], v[28:29], v[70:71]
	s_waitcnt vmcnt(6)
	s_nop 1
	v_mov_b32_e32 v84, v220
	v_mov_b32_e32 v85, v221
	v_mov_b32_e32 v86, v222
	v_mov_b32_e32 v87, v223
	v_lshlrev_b32_e32 v110, 16, v84
	v_and_b32_e32 v127, 0xffff0000, v84
	v_lshlrev_b32_e32 v128, 16, v85
	v_and_b32_e32 v129, 0xffff0000, v85
	v_pk_fma_f32 v[30:31], v[64:65], v[30:31], v[68:69]
	v_sub_f32_e32 v85, v129, v106
	v_sub_f32_e32 v84, v128, v106
	v_sub_f32_e32 v121, v127, v106
	v_sub_f32_e32 v120, v110, v106
	v_cndmask_b32_e64 v27, v27, v58, s[30:31]
	v_cndmask_b32_e64 v26, v26, v56, s[30:31]
	v_cndmask_b32_e64 v25, v25, v62, s[30:31]
	v_cndmask_b32_e64 v24, v24, v60, s[30:31]
	v_cndmask_b32_e64 v31, v31, v122, s[30:31]
	v_cndmask_b32_e64 v30, v30, v82, s[30:31]
	v_cndmask_b32_e64 v29, v29, v126, s[30:31]
	v_cndmask_b32_e64 v28, v28, v123, s[30:31]
	v_pk_mul_f32 v[120:121], v[104:105], v[120:121] op_sel_hi:[0,1]
	v_pk_mul_f32 v[84:85], v[104:105], v[84:85] op_sel_hi:[0,1]
	v_pk_fma_f32 v[14:15], v[24:25], s[70:71], v[14:15] op_sel_hi:[1,0,1]
	v_pk_fma_f32 v[12:13], v[26:27], s[70:71], v[12:13] op_sel_hi:[1,0,1]
	v_pk_fma_f32 v[10:11], v[28:29], s[70:71], v[10:11] op_sel_hi:[1,0,1]
	v_pk_fma_f32 v[8:9], v[30:31], s[70:71], v[8:9] op_sel_hi:[1,0,1]
	v_cvt_pk_bf16_f32 v24, v12, v13
	v_cvt_pk_bf16_f32 v25, v14, v15
	v_lshlrev_b32_e32 v28, 16, v86
	v_cvt_pk_bf16_f32 v26, v8, v9
	v_cvt_pk_bf16_f32 v27, v10, v11
	global_store_dwordx4 v[124:125], v[24:27], off nt
	v_and_b32_e32 v29, 0xffff0000, v86
	v_and_b32_e32 v30, 0xffff0000, v87
	v_pk_fma_f32 v[24:25], v[74:75], v[84:85], v[78:79]
	v_pk_fma_f32 v[26:27], v[72:73], v[120:121], v[76:77]
	v_cndmask_b32_e64 v25, v25, v129, s[30:31]
	v_cndmask_b32_e64 v27, v27, v127, s[30:31]
	v_cndmask_b32_e64 v26, v26, v110, s[30:31]
	v_cndmask_b32_e64 v24, v24, v128, s[30:31]
	v_lshlrev_b32_e32 v72, 16, v87
	v_pk_fma_f32 v[6:7], v[24:25], s[70:71], v[6:7] op_sel_hi:[1,0,1]
	v_pk_fma_f32 v[4:5], v[26:27], s[70:71], v[4:5] op_sel_hi:[1,0,1]
	v_sub_f32_e32 v25, v30, v106
	v_sub_f32_e32 v24, v72, v106
	v_sub_f32_e32 v27, v29, v106
	v_sub_f32_e32 v26, v28, v106
	v_pk_mul_f32 v[26:27], v[104:105], v[26:27] op_sel_hi:[0,1]
	v_pk_mul_f32 v[24:25], v[104:105], v[24:25] op_sel_hi:[0,1]
	v_pk_fma_f32 v[24:25], v[66:67], v[24:25], v[70:71]
	v_pk_fma_f32 v[26:27], v[64:65], v[26:27], v[68:69]
	v_mov_b32_e32 v104, v118
	v_mov_b32_e32 v60, v119
	v_mov_b32_e32 v106, v116
	v_mov_b32_e32 v62, v117
	v_cndmask_b32_e64 v27, v27, v29, s[30:31]
	v_cndmask_b32_e64 v26, v26, v28, s[30:31]
	v_cndmask_b32_e64 v25, v25, v30, s[30:31]
	v_pk_add_f32 v[28:29], v[104:105], v[60:61]
	v_pk_add_f32 v[30:31], v[106:107], v[62:63]
	v_mov_b32_e32 v108, v90
	v_mov_b32_e32 v56, v91
	v_mov_b32_e32 v110, v88
	v_mov_b32_e32 v58, v89
	v_pk_add_f32 v[28:29], v[28:29], v[30:31]
	v_pk_add_f32 v[30:31], v[108:109], v[56:57]
	v_pk_add_f32 v[56:57], v[110:111], v[58:59]
	v_mov_b32_e32 v82, v175
	v_pk_add_f32 v[30:31], v[30:31], v[56:57]
	v_pk_add_f32 v[56:57], v[112:113], v[114:115]
	v_pk_add_f32 v[28:29], v[28:29], v[30:31]
	v_pk_add_f32 v[30:31], v[92:93], v[94:95]
	v_cndmask_b32_e64 v24, v24, v72, s[30:31]
	v_pk_add_f32 v[30:31], v[30:31], v[56:57]
	v_pk_fma_f32 v[2:3], v[24:25], s[70:71], v[2:3] op_sel_hi:[1,0,1]
	v_pk_add_f32 v[30:31], v[30:31], v[82:83]
	v_pk_fma_f32 v[0:1], v[26:27], s[70:71], v[0:1] op_sel_hi:[1,0,1]
	v_pk_add_f32 v[30:31], v[28:29], v[30:31]
	ds_bpermute_b32 v56, v178, v30
	ds_bpermute_b32 v57, v178, v31
	v_cvt_pk_bf16_f32 v28, v4, v5
	v_cvt_pk_bf16_f32 v29, v6, v7
	s_waitcnt lgkmcnt(0)
	v_pk_add_f32 v[24:25], v[30:31], v[56:57]
	ds_bpermute_b32 v26, v176, v24
	ds_bpermute_b32 v27, v176, v25
	v_cvt_pk_bf16_f32 v30, v0, v1
	v_cvt_pk_bf16_f32 v31, v2, v3
	global_store_dwordx4 v[80:81], v[28:31], off nt
	s_and_saveexec_b64 s[10:11], s[26:27]
	s_cbranch_execz .LBB0_1081
	v_lshlrev_b64 v[28:29], 7, v[102:103]
	v_lshl_add_u64 v[28:29], s[50:51], 0, v[28:29]
	s_waitcnt lgkmcnt(0)
	v_pk_add_f32 v[24:25], v[24:25], v[26:27]
	global_store_dwordx2 v[28:29], v[24:25], off

.LBB0_1351:
	s_add_u32 s10, s42, 0xfff00080
	s_addc_u32 s11, s43, -1
	s_add_i32 s45, 0, 0x10000
	v_add_u32_e32 v76, s45, v222
	ds_read_b128 v[64:67], v76
	ds_read_b128 v[68:71], v76 offset:1024
	ds_read_b128 v[72:75], v76 offset:2048
	ds_read_b128 v[76:79], v76 offset:3072
	s_cmp_eq_u32 s44, 60
	s_cselect_b32 s13, s16, s11
	s_cselect_b32 s12, s17, s10
	s_cselect_b32 s11, s20, s37
	s_cselect_b32 s10, s21, s35
	v_lshl_add_u64 v[168:169], s[42:43], 0, v[188:189]
	s_add_i32 m0, s54, 0xc000
	ds_read_b128 v[96:99], v227
	ds_read_b128 v[100:103], v227 offset:1024
	ds_read_b128 v[104:107], v227 offset:2048
	ds_read_b128 v[108:111], v227 offset:3072
	ds_read_b128 v[160:163], v227 offset:4096
	ds_read_b128 v[164:167], v227 offset:5120
	ds_read_b128 v[192:195], v227 offset:6144
	ds_read_b128 v[196:199], v227 offset:7168
	global_load_lds_dwordx4 v[168:169], off
	v_lshl_add_u64 v[168:169], s[42:43], 0, v[190:191]
	s_add_i32 m0, s54, 0xe000
	s_nop 0
	global_load_lds_dwordx4 v[168:169], off
	s_waitcnt lgkmcnt(8)
	s_barrier
	s_waitcnt lgkmcnt(0)
	s_setprio 1
	s_waitcnt lgkmcnt(0)
	v_mfma_f32_16x16x32_bf16 v[156:159], v[64:67], v[96:99], v[156:159]
	v_mfma_f32_16x16x32_bf16 v[152:155], v[72:75], v[96:99], v[152:155]
	v_mfma_f32_16x16x32_bf16 v[148:151], v[64:67], v[104:107], v[148:151]
	v_mfma_f32_16x16x32_bf16 v[144:147], v[72:75], v[104:107], v[144:147]
	v_mfma_f32_16x16x32_bf16 v[140:143], v[64:67], v[160:163], v[140:143]
	v_mfma_f32_16x16x32_bf16 v[136:139], v[72:75], v[160:163], v[136:139]
	v_mfma_f32_16x16x32_bf16 v[132:135], v[64:67], v[192:195], v[132:135]
	v_mfma_f32_16x16x32_bf16 v[128:131], v[72:75], v[192:195], v[128:131]
	v_mfma_f32_16x16x32_bf16 v[156:159], v[68:71], v[100:103], v[156:159]
	v_mfma_f32_16x16x32_bf16 v[152:155], v[76:79], v[100:103], v[152:155]
	v_mfma_f32_16x16x32_bf16 v[148:151], v[68:71], v[108:111], v[148:151]
	v_mfma_f32_16x16x32_bf16 v[144:147], v[76:79], v[108:111], v[144:147]
	v_mfma_f32_16x16x32_bf16 v[140:143], v[68:71], v[164:167], v[140:143]
	v_mfma_f32_16x16x32_bf16 v[136:139], v[76:79], v[164:167], v[136:139]
	v_mfma_f32_16x16x32_bf16 v[132:135], v[68:71], v[196:199], v[132:135]
	v_mfma_f32_16x16x32_bf16 v[128:131], v[76:79], v[196:199], v[128:131]
	s_setprio 0
	s_barrier
	s_add_i32 s78, 0, 0x14000
	v_add_u32_e32 v168, s78, v222
	s_add_i32 s45, s45, s47
	ds_read_b128 v[200:203], v168
	ds_read_b128 v[204:207], v168 offset:1024
	ds_read_b128 v[208:211], v168 offset:2048
	ds_read_b128 v[212:215], v168 offset:3072
	v_lshl_add_u64 v[168:169], s[10:11], 0, v[174:175]
	s_mov_b32 m0, s45
	v_lshl_add_u64 v[172:173], s[10:11], 0, v[182:183]
	global_load_lds_dwordx4 v[168:169], off
	s_add_i32 m0, s45, 0x2000
	s_nop 0
	global_load_lds_dwordx4 v[172:173], off
	s_barrier
	s_waitcnt lgkmcnt(0)
	s_setprio 1
	s_waitcnt lgkmcnt(0)
	v_mfma_f32_16x16x32_bf16 v[124:127], v[200:203], v[96:99], v[124:127]
	v_mfma_f32_16x16x32_bf16 v[96:99], v[208:211], v[96:99], v[120:123]
	v_mfma_f32_16x16x32_bf16 v[92:95], v[200:203], v[160:163], v[92:95]
	v_mfma_f32_16x16x32_bf16 v[88:91], v[208:211], v[160:163], v[88:91]
	v_mfma_f32_16x16x32_bf16 v[84:87], v[200:203], v[192:195], v[84:87]
	v_mfma_f32_16x16x32_bf16 v[80:83], v[208:211], v[192:195], v[80:83]
	v_mfma_f32_16x16x32_bf16 v[124:127], v[204:207], v[100:103], v[124:127]
	v_mfma_f32_16x16x32_bf16 v[96:99], v[212:215], v[100:103], v[96:99]
	v_mfma_f32_16x16x32_bf16 v[100:103], v[200:203], v[104:107], v[116:119]
	v_mfma_f32_16x16x32_bf16 v[104:107], v[208:211], v[104:107], v[112:115]
	v_mfma_f32_16x16x32_bf16 v[92:95], v[204:207], v[164:167], v[92:95]
	v_mfma_f32_16x16x32_bf16 v[88:91], v[212:215], v[164:167], v[88:91]
	v_mfma_f32_16x16x32_bf16 v[84:87], v[204:207], v[196:199], v[84:87]
	v_mfma_f32_16x16x32_bf16 v[80:83], v[212:215], v[196:199], v[80:83]
	v_mfma_f32_16x16x32_bf16 v[100:103], v[204:207], v[108:111], v[100:103]
	v_mfma_f32_16x16x32_bf16 v[104:107], v[212:215], v[108:111], v[104:107]
	s_setprio 0
	s_mov_b32 m0, s54
	v_lshl_add_u64 v[216:217], s[12:13], 0, v[186:187]
	s_barrier
	ds_read_b128 v[108:111], v227 offset:16384
	ds_read_b128 v[112:115], v227 offset:17408
	ds_read_b128 v[116:119], v227 offset:18432
	ds_read_b128 v[120:123], v227 offset:19456
	ds_read_b128 v[160:163], v227 offset:20480
	ds_read_b128 v[164:167], v227 offset:21504
	ds_read_b128 v[192:195], v227 offset:22528
	ds_read_b128 v[196:199], v227 offset:23552
	global_load_lds_dwordx4 v[216:217], off
	v_lshl_add_u64 v[238:239], s[12:13], 0, v[184:185]
	s_mov_b32 m0, s55
	s_nop 0
	global_load_lds_dwordx4 v[238:239], off
	s_barrier
	s_waitcnt lgkmcnt(0)
	s_setprio 1
	s_waitcnt lgkmcnt(0)
	v_mfma_f32_16x16x32_bf16 v[60:63], v[64:67], v[108:111], v[60:63]
	v_mfma_f32_16x16x32_bf16 v[56:59], v[72:75], v[108:111], v[56:59]
	v_mfma_f32_16x16x32_bf16 v[52:55], v[64:67], v[116:119], v[52:55]
	v_mfma_f32_16x16x32_bf16 v[48:51], v[72:75], v[116:119], v[48:51]
	v_mfma_f32_16x16x32_bf16 v[44:47], v[64:67], v[160:163], v[44:47]
	v_mfma_f32_16x16x32_bf16 v[40:43], v[72:75], v[160:163], v[40:43]
	v_mfma_f32_16x16x32_bf16 v[36:39], v[64:67], v[192:195], v[36:39]
	v_mfma_f32_16x16x32_bf16 v[32:35], v[72:75], v[192:195], v[32:35]
	v_mfma_f32_16x16x32_bf16 v[60:63], v[68:71], v[112:115], v[60:63]
	v_mfma_f32_16x16x32_bf16 v[56:59], v[76:79], v[112:115], v[56:59]
	v_mfma_f32_16x16x32_bf16 v[52:55], v[68:71], v[120:123], v[52:55]
	v_mfma_f32_16x16x32_bf16 v[48:51], v[76:79], v[120:123], v[48:51]
	v_mfma_f32_16x16x32_bf16 v[44:47], v[68:71], v[164:167], v[44:47]
	v_mfma_f32_16x16x32_bf16 v[40:43], v[76:79], v[164:167], v[40:43]
	v_mfma_f32_16x16x32_bf16 v[36:39], v[68:71], v[196:199], v[36:39]
	v_mfma_f32_16x16x32_bf16 v[32:35], v[76:79], v[196:199], v[32:35]
	s_setprio 0
	s_barrier
	s_add_u32 s76, s10, 0x100000
	s_addc_u32 s77, s11, 0
	s_add_i32 s45, s78, s47
	v_lshl_add_u64 v[64:65], s[76:77], 0, v[174:175]
	s_mov_b32 m0, s45
	s_nop 0
	global_load_lds_dwordx4 v[64:65], off
	v_lshl_add_u64 v[64:65], s[76:77], 0, v[182:183]
	s_add_i32 m0, s45, 0x2000
	s_nop 0
	global_load_lds_dwordx4 v[64:65], off
	s_waitcnt vmcnt(6)
	s_barrier
	s_setprio 1
	v_mfma_f32_16x16x32_bf16 v[28:31], v[200:203], v[108:111], v[28:31]
	v_mfma_f32_16x16x32_bf16 v[24:27], v[208:211], v[108:111], v[24:27]
	v_mfma_f32_16x16x32_bf16 v[20:23], v[200:203], v[116:119], v[20:23]
	v_mfma_f32_16x16x32_bf16 v[16:19], v[208:211], v[116:119], v[16:19]
	v_mfma_f32_16x16x32_bf16 v[12:15], v[200:203], v[160:163], v[12:15]
	v_mfma_f32_16x16x32_bf16 v[8:11], v[208:211], v[160:163], v[8:11]
	v_mfma_f32_16x16x32_bf16 v[4:7], v[200:203], v[192:195], v[4:7]
	v_mfma_f32_16x16x32_bf16 v[0:3], v[208:211], v[192:195], v[0:3]
	v_mfma_f32_16x16x32_bf16 v[28:31], v[204:207], v[112:115], v[28:31]
	v_mfma_f32_16x16x32_bf16 v[24:27], v[212:215], v[112:115], v[24:27]
	v_mfma_f32_16x16x32_bf16 v[20:23], v[204:207], v[120:123], v[20:23]
	v_mfma_f32_16x16x32_bf16 v[16:19], v[212:215], v[120:123], v[16:19]
	v_mfma_f32_16x16x32_bf16 v[12:15], v[204:207], v[164:167], v[12:15]
	v_mfma_f32_16x16x32_bf16 v[8:11], v[212:215], v[164:167], v[8:11]
	v_mfma_f32_16x16x32_bf16 v[4:7], v[204:207], v[196:199], v[4:7]
	v_mfma_f32_16x16x32_bf16 v[0:3], v[212:215], v[196:199], v[0:3]
	s_setprio 0
	s_add_i32 s45, 0, 0x18000
	v_add_u32_e32 v76, s45, v222
	s_barrier
	ds_read_b128 v[64:67], v76
	ds_read_b128 v[68:71], v76 offset:1024
	ds_read_b128 v[72:75], v76 offset:2048
	ds_read_b128 v[76:79], v76 offset:3072
	s_add_u32 s12, s12, 0x100000
	s_addc_u32 s13, s13, 0
	s_mov_b32 m0, s58
	v_lshl_add_u64 v[116:117], s[12:13], 0, v[186:187]
	ds_read_b128 v[108:111], v227 offset:32768
	ds_read_b128 v[112:115], v227 offset:33792
	ds_read_b128 v[160:163], v227 offset:34816
	ds_read_b128 v[164:167], v227 offset:35840
	ds_read_b128 v[192:195], v227 offset:36864
	ds_read_b128 v[196:199], v227 offset:37888
	ds_read_b128 v[200:203], v227 offset:38912
	ds_read_b128 v[204:207], v227 offset:39936
	global_load_lds_dwordx4 v[116:117], off
	v_lshl_add_u64 v[116:117], s[12:13], 0, v[184:185]
	s_mov_b32 m0, s59
	s_nop 0
	global_load_lds_dwordx4 v[116:117], off
	s_waitcnt lgkmcnt(8)
	s_barrier
	s_waitcnt lgkmcnt(0)
	s_setprio 1
	s_waitcnt lgkmcnt(0)
	v_mfma_f32_16x16x32_bf16 v[116:119], v[64:67], v[108:111], v[156:159]
	v_mfma_f32_16x16x32_bf16 v[156:159], v[68:71], v[112:115], v[116:119]
	v_mfma_f32_16x16x32_bf16 v[116:119], v[72:75], v[108:111], v[152:155]
	v_mfma_f32_16x16x32_bf16 v[152:155], v[76:79], v[112:115], v[116:119]
	v_mfma_f32_16x16x32_bf16 v[116:119], v[64:67], v[160:163], v[148:151]
	v_mfma_f32_16x16x32_bf16 v[148:151], v[68:71], v[164:167], v[116:119]
	v_mfma_f32_16x16x32_bf16 v[116:119], v[72:75], v[160:163], v[144:147]
	v_mfma_f32_16x16x32_bf16 v[144:147], v[76:79], v[164:167], v[116:119]
	v_mfma_f32_16x16x32_bf16 v[116:119], v[64:67], v[192:195], v[140:143]
	v_mfma_f32_16x16x32_bf16 v[140:143], v[68:71], v[196:199], v[116:119]
	v_mfma_f32_16x16x32_bf16 v[116:119], v[72:75], v[192:195], v[136:139]
	v_mfma_f32_16x16x32_bf16 v[136:139], v[76:79], v[196:199], v[116:119]
	v_mfma_f32_16x16x32_bf16 v[116:119], v[64:67], v[200:203], v[132:135]
	v_mfma_f32_16x16x32_bf16 v[132:135], v[68:71], v[204:207], v[116:119]
	v_mfma_f32_16x16x32_bf16 v[116:119], v[72:75], v[200:203], v[128:131]
	v_mfma_f32_16x16x32_bf16 v[128:131], v[76:79], v[204:207], v[116:119]
	s_setprio 0
	s_barrier
	s_add_i32 s12, 0, 0x1c000
	s_nop 3
	v_add_u32_e32 v116, s12, v222
	s_add_i32 s13, s45, s47
	ds_read_b128 v[208:211], v116
	ds_read_b128 v[212:215], v116 offset:1024
	ds_read_b128 v[228:231], v116 offset:2048
	ds_read_b128 v[232:235], v116 offset:3072
	v_lshl_add_u64 v[116:117], v[168:169], 0, s[8:9]
	s_mov_b32 m0, s13
	s_nop 0
	global_load_lds_dwordx4 v[116:117], off
	v_lshl_add_u64 v[116:117], v[172:173], 0, s[8:9]
	s_add_i32 m0, s13, 0x2000
	s_nop 0
	global_load_lds_dwordx4 v[116:117], off
	s_barrier
	s_waitcnt lgkmcnt(0)
	s_setprio 1
	s_waitcnt lgkmcnt(0)
	v_mfma_f32_16x16x32_bf16 v[96:99], v[228:231], v[108:111], v[96:99]
	v_mfma_f32_16x16x32_bf16 v[116:119], v[208:211], v[108:111], v[124:127]
	v_mfma_f32_16x16x32_bf16 v[120:123], v[232:235], v[112:115], v[96:99]
	v_mfma_f32_16x16x32_bf16 v[96:99], v[208:211], v[160:163], v[100:103]
	v_mfma_f32_16x16x32_bf16 v[124:127], v[212:215], v[112:115], v[116:119]
	v_mfma_f32_16x16x32_bf16 v[116:119], v[212:215], v[164:167], v[96:99]
	v_mfma_f32_16x16x32_bf16 v[96:99], v[228:231], v[160:163], v[104:107]
	v_mfma_f32_16x16x32_bf16 v[92:95], v[208:211], v[192:195], v[92:95]
	v_mfma_f32_16x16x32_bf16 v[88:91], v[228:231], v[192:195], v[88:91]
	v_mfma_f32_16x16x32_bf16 v[84:87], v[208:211], v[200:203], v[84:87]
	v_mfma_f32_16x16x32_bf16 v[80:83], v[228:231], v[200:203], v[80:83]
	v_mfma_f32_16x16x32_bf16 v[112:115], v[232:235], v[164:167], v[96:99]
	v_mfma_f32_16x16x32_bf16 v[92:95], v[212:215], v[196:199], v[92:95]
	v_mfma_f32_16x16x32_bf16 v[88:91], v[232:235], v[196:199], v[88:91]
	v_mfma_f32_16x16x32_bf16 v[84:87], v[212:215], v[204:207], v[84:87]
	v_mfma_f32_16x16x32_bf16 v[80:83], v[232:235], v[204:207], v[80:83]
	s_setprio 0
	s_mov_b32 m0, s62
	v_lshl_add_u64 v[168:169], v[216:217], 0, s[8:9]
	s_barrier
	ds_read_b128 v[96:99], v227 offset:49152
	ds_read_b128 v[100:103], v227 offset:50176
	ds_read_b128 v[104:107], v227 offset:51200
	ds_read_b128 v[108:111], v227 offset:52224
	ds_read_b128 v[160:163], v227 offset:53248
	ds_read_b128 v[164:167], v227 offset:54272
	ds_read_b128 v[192:195], v227 offset:55296
	ds_read_b128 v[196:199], v227 offset:56320
	global_load_lds_dwordx4 v[168:169], off
	v_lshl_add_u64 v[168:169], v[238:239], 0, s[8:9]
	s_mov_b32 m0, s63
	s_nop 0
	global_load_lds_dwordx4 v[168:169], off
	s_barrier
	s_waitcnt lgkmcnt(0)
	s_setprio 1
	s_waitcnt lgkmcnt(0)
	v_mfma_f32_16x16x32_bf16 v[60:63], v[64:67], v[96:99], v[60:63]
	v_mfma_f32_16x16x32_bf16 v[56:59], v[72:75], v[96:99], v[56:59]
	v_mfma_f32_16x16x32_bf16 v[52:55], v[64:67], v[104:107], v[52:55]
	v_mfma_f32_16x16x32_bf16 v[48:51], v[72:75], v[104:107], v[48:51]
	v_mfma_f32_16x16x32_bf16 v[44:47], v[64:67], v[160:163], v[44:47]
	v_mfma_f32_16x16x32_bf16 v[40:43], v[72:75], v[160:163], v[40:43]
	v_mfma_f32_16x16x32_bf16 v[36:39], v[64:67], v[192:195], v[36:39]
	v_mfma_f32_16x16x32_bf16 v[32:35], v[72:75], v[192:195], v[32:35]
	v_mfma_f32_16x16x32_bf16 v[60:63], v[68:71], v[100:103], v[60:63]
	v_mfma_f32_16x16x32_bf16 v[56:59], v[76:79], v[100:103], v[56:59]
	v_mfma_f32_16x16x32_bf16 v[52:55], v[68:71], v[108:111], v[52:55]
	v_mfma_f32_16x16x32_bf16 v[48:51], v[76:79], v[108:111], v[48:51]
	v_mfma_f32_16x16x32_bf16 v[44:47], v[68:71], v[164:167], v[44:47]
	v_mfma_f32_16x16x32_bf16 v[40:43], v[76:79], v[164:167], v[40:43]
	v_mfma_f32_16x16x32_bf16 v[36:39], v[68:71], v[196:199], v[36:39]
	v_mfma_f32_16x16x32_bf16 v[32:35], v[76:79], v[196:199], v[32:35]
	s_setprio 0
	s_barrier
	s_add_u32 s10, s10, 0x100080
	s_addc_u32 s11, s11, 0
	s_add_i32 s12, s12, s47
	v_lshl_add_u64 v[64:65], s[10:11], 0, v[174:175]
	s_mov_b32 m0, s12
	s_nop 0
	global_load_lds_dwordx4 v[64:65], off
	v_lshl_add_u64 v[64:65], s[10:11], 0, v[182:183]
	s_add_i32 m0, s12, 0x2000
	s_nop 0
	global_load_lds_dwordx4 v[64:65], off
	s_waitcnt vmcnt(6)
	s_barrier
	s_setprio 1
	v_mfma_f32_16x16x32_bf16 v[28:31], v[208:211], v[96:99], v[28:31]
	v_mfma_f32_16x16x32_bf16 v[24:27], v[228:231], v[96:99], v[24:27]
	v_mfma_f32_16x16x32_bf16 v[20:23], v[208:211], v[104:107], v[20:23]
	v_mfma_f32_16x16x32_bf16 v[16:19], v[228:231], v[104:107], v[16:19]
	v_mfma_f32_16x16x32_bf16 v[12:15], v[208:211], v[160:163], v[12:15]
	v_mfma_f32_16x16x32_bf16 v[8:11], v[228:231], v[160:163], v[8:11]
	v_mfma_f32_16x16x32_bf16 v[4:7], v[208:211], v[192:195], v[4:7]
	v_mfma_f32_16x16x32_bf16 v[0:3], v[228:231], v[192:195], v[0:3]
	v_mfma_f32_16x16x32_bf16 v[28:31], v[212:215], v[100:103], v[28:31]
	v_mfma_f32_16x16x32_bf16 v[24:27], v[232:235], v[100:103], v[24:27]
	v_mfma_f32_16x16x32_bf16 v[20:23], v[212:215], v[108:111], v[20:23]
	v_mfma_f32_16x16x32_bf16 v[16:19], v[232:235], v[108:111], v[16:19]
	v_mfma_f32_16x16x32_bf16 v[12:15], v[212:215], v[164:167], v[12:15]
	v_mfma_f32_16x16x32_bf16 v[8:11], v[232:235], v[164:167], v[8:11]
	v_mfma_f32_16x16x32_bf16 v[4:7], v[212:215], v[196:199], v[4:7]
	v_mfma_f32_16x16x32_bf16 v[0:3], v[232:235], v[196:199], v[0:3]
	s_setprio 0
	s_add_i32 s44, s44, 2
	s_add_u32 s42, s42, 0x100
	s_addc_u32 s43, s43, 0
	s_add_u32 s35, s35, 0x100
	s_addc_u32 s37, s37, 0
	s_cmp_gt_u32 s44, 61
	s_barrier
	s_cbranch_scc0 .LBB0_1351
	s_nop 15
	s_nop 15
	s_waitcnt vmcnt(6)
	v_lshl_add_u32 v64, v237, 4, s47
	v_add_u32_e32 v65, 0x10000, v64
	ds_write_b128 v64, v[0:3] offset:49152
	ds_write_b128 v64, v[4:7] offset:57344
	ds_write_b128 v65, v[8:11]
	ds_write_b128 v65, v[12:15] offset:8192
	ds_write_b128 v64, v[16:19]
	ds_write_b128 v64, v[20:23] offset:8192
	ds_write_b128 v65, v[24:27] offset:16384
	ds_write_b128 v65, v[28:31] offset:24576
	s_mov_b64 s[10:11], s[0:1]
	s_load_dwordx4 s[76:79], s[10:11], 0x98
	s_load_dwordx2 s[44:45], s[10:11], 0xd0
	s_mov_b32 s10, s74
	s_lshl_b32 s10, s10, 10
	s_ashr_i32 s11, s10, 31
	s_lshl_b64 s[10:11], s[10:11], 2
	s_waitcnt lgkmcnt(0)
	s_add_u32 s12, s76, s10
	s_addc_u32 s13, s77, s11
	s_add_u32 s10, s78, s10
	s_addc_u32 s11, s79, s11
	s_lshl_b32 s16, s26, 11
	v_lshl_add_u32 v192, s27, 8, v221
	v_lshl_or_b32 v196, s75, 8, v223
	s_add_u32 s42, s44, 0x2a00000
	v_ashrrev_i32_e32 v193, 31, v192
	v_ashrrev_i32_e32 v197, 31, v196
	s_addc_u32 s43, s45, 0
	v_lshlrev_b64 v[230:231], 11, v[192:193]
	v_or_b32_e32 v198, 16, v192
	v_lshl_add_u64 v[202:203], s[42:43], 0, v[230:231]
	v_lshlrev_b64 v[64:65], 1, v[196:197]
	v_ashrrev_i32_e32 v199, 31, v198
	v_lshl_add_u64 v[208:209], v[202:203], 0, v[64:65]
	v_lshl_add_u64 v[194:195], s[42:43], 0, v[64:65]
	v_lshlrev_b64 v[210:211], 11, v[198:199]
	v_lshl_add_u64 v[234:235], v[194:195], 0, v[210:211]
	v_lshlrev_b64 v[64:65], 2, v[196:197]
	v_lshl_add_u64 v[76:77], s[10:11], 0, v[64:65]
	v_lshl_add_u64 v[68:69], s[12:13], 0, v[64:65]
	global_load_dwordx4 v[96:99], v[76:77], off
	global_load_dwordx4 v[100:103], v[68:69], off
	global_load_dwordx4 v[104:107], v[68:69], off offset:16
	global_load_dwordx4 v[108:111], v[76:77], off offset:16
	v_add_u32_e32 v228, s16, v224
	global_load_dwordx4 v[64:67], v[68:69], off offset:528
	global_load_dwordx4 v[72:75], v[68:69], off offset:512
	s_nop 0
	global_load_dwordx4 v[68:71], v[76:77], off offset:528
	s_nop 0
	global_load_dwordx4 v[76:79], v[76:77], off offset:512
	s_waitcnt lgkmcnt(0)
	s_mov_b32 s101, 0
	s_mov_b32 s100, 0x8000
	v_lshl_add_u64 v[160:161], v[208:209], 0, s[100:101]
	s_mov_b32 s100, 0x10000
	v_lshl_add_u64 v[162:163], v[208:209], 0, s[100:101]
	s_mov_b32 s100, 0x18000
	v_lshl_add_u64 v[164:165], v[208:209], 0, s[100:101]
	global_load_dwordx4 v[0:3], v[208:209], off
	global_load_dwordx4 v[4:7], v[160:161], off
	global_load_dwordx4 v[8:11], v[162:163], off
	global_load_dwordx4 v[12:15], v[164:165], off
	global_load_dwordx4 v[16:19], v[208:209], off offset:256
	global_load_dwordx4 v[20:23], v[160:161], off offset:256
	global_load_dwordx4 v[24:27], v[162:163], off offset:256
	global_load_dwordx4 v[28:31], v[164:165], off offset:256
	ds_read2_b64 v[164:167], v228 offset1:16
	ds_read2_b64 v[160:163], v228 offset0:32 offset1:48
	v_lshl_add_u64 v[244:245], v[194:195], 0, v[230:231]
	v_or_b32_e32 v200, 32, v192
	v_ashrrev_i32_e32 v201, 31, v200
	v_lshlrev_b64 v[212:213], 11, v[200:201]
	v_lshl_add_u64 v[252:253], v[194:195], 0, v[212:213]
	s_lshl_b32 s10, s75, 3
	s_or_b32 s10, s10, s68
	s_ashr_i32 s11, s10, 31
	s_lshl_b64 s[10:11], s[10:11], 2
	s_add_u32 s10, s44, s10
	s_addc_u32 s11, s45, s11
	s_add_u32 s44, s10, 0xed84000
	s_addc_u32 s45, s11, 0
	s_waitcnt vmcnt(7)
	s_nop 1
	v_mov_b32_e32 v204, v0
	v_mov_b32_e32 v205, v1
	v_mov_b32_e32 v206, v2
	v_mov_b32_e32 v207, v3
	v_lshlrev_b32_e32 v168, 16, v204
	v_and_b32_e32 v169, 0xffff0000, v204
	v_lshlrev_b32_e32 v172, 16, v205
	v_and_b32_e32 v173, 0xffff0000, v205
	v_lshlrev_b32_e32 v229, 16, v206
	v_and_b32_e32 v230, 0xffff0000, v206
	v_lshlrev_b32_e32 v231, 16, v207
	v_and_b32_e32 v232, 0xffff0000, v207
	s_waitcnt vmcnt(6)
	s_nop 1
	v_mov_b32_e32 v214, v4
	v_mov_b32_e32 v215, v5
	v_mov_b32_e32 v216, v6
	v_mov_b32_e32 v217, v7
	v_lshlrev_b32_e32 v233, 16, v214
	v_and_b32_e32 v238, 0xffff0000, v214
	v_lshlrev_b32_e32 v239, 16, v215
	v_and_b32_e32 v246, 0xffff0000, v215
	s_waitcnt lgkmcnt(1)
	v_sub_f32_e32 v205, v169, v164
	v_sub_f32_e32 v204, v168, v164
	v_sub_f32_e32 v207, v173, v164
	v_sub_f32_e32 v206, v172, v164
	v_sub_f32_e32 v215, v230, v164
	v_sub_f32_e32 v214, v229, v164
	v_lshlrev_b32_e32 v247, 16, v216
	v_and_b32_e32 v248, 0xffff0000, v216
	v_lshlrev_b32_e32 v249, 16, v217
	v_and_b32_e32 v250, 0xffff0000, v217
	v_sub_f32_e32 v217, v232, v164
	v_sub_f32_e32 v216, v231, v164
	v_pk_mul_f32 v[206:207], v[164:165], v[206:207] op_sel:[1,0]
	v_pk_mul_f32 v[204:205], v[164:165], v[204:205] op_sel:[1,0]
	v_pk_mul_f32 v[214:215], v[164:165], v[214:215] op_sel:[1,0]
	v_pk_mul_f32 v[216:217], v[164:165], v[216:217] op_sel:[1,0]
	v_pk_fma_f32 v[204:205], v[100:101], v[204:205], v[96:97]
	v_pk_fma_f32 v[206:207], v[102:103], v[206:207], v[98:99]
	v_pk_fma_f32 v[214:215], v[104:105], v[214:215], v[108:109]
	v_pk_fma_f32 v[216:217], v[106:107], v[216:217], v[110:111]
	v_pk_fma_f32 v[158:159], v[206:207], s[70:71], v[158:159] op_sel_hi:[1,0,1]
	v_pk_fma_f32 v[206:207], v[204:205], s[70:71], v[156:157] op_sel_hi:[1,0,1]
	v_pk_fma_f32 v[204:205], v[214:215], s[70:71], v[152:153] op_sel_hi:[1,0,1]
	v_cvt_pk_bf16_f32 v152, v206, v207
	v_cvt_pk_bf16_f32 v153, v158, v159
	v_pk_fma_f32 v[156:157], v[216:217], s[70:71], v[154:155] op_sel_hi:[1,0,1]
	v_cvt_pk_bf16_f32 v154, v204, v205
	v_sub_f32_e32 v231, v238, v166
	v_cvt_pk_bf16_f32 v155, v156, v157
	global_store_dwordx4 v[244:245], v[152:155], off nt
	v_sub_f32_e32 v230, v233, v166
	v_sub_f32_e32 v233, v246, v166
	v_sub_f32_e32 v153, v248, v166
	v_sub_f32_e32 v152, v247, v166
	v_pk_mul_f32 v[152:153], v[166:167], v[152:153] op_sel:[1,0]
	v_sub_f32_e32 v232, v239, v166
	v_pk_fma_f32 v[152:153], v[104:105], v[152:153], v[108:109]
	v_pk_mul_f32 v[232:233], v[166:167], v[232:233] op_sel:[1,0]
	v_pk_fma_f32 v[152:153], v[152:153], s[70:71], v[144:145] op_sel_hi:[1,0,1]
	v_or_b32_e32 v144, 48, v192
	v_pk_mul_f32 v[230:231], v[166:167], v[230:231] op_sel:[1,0]
	v_sub_f32_e32 v155, v250, v166
	v_sub_f32_e32 v154, v249, v166
	v_ashrrev_i32_e32 v145, 31, v144
	v_pk_fma_f32 v[230:231], v[100:101], v[230:231], v[96:97]
	v_pk_fma_f32 v[232:233], v[102:103], v[232:233], v[98:99]
	v_pk_mul_f32 v[154:155], v[166:167], v[154:155] op_sel:[1,0]
	v_lshlrev_b64 v[216:217], 11, v[144:145]
	v_pk_fma_f32 v[150:151], v[232:233], s[70:71], v[150:151] op_sel_hi:[1,0,1]
	v_pk_fma_f32 v[148:149], v[230:231], s[70:71], v[148:149] op_sel_hi:[1,0,1]
	v_pk_fma_f32 v[154:155], v[106:107], v[154:155], v[110:111]
	v_lshl_add_u64 v[214:215], v[194:195], 0, v[216:217]
	v_pk_fma_f32 v[146:147], v[154:155], s[70:71], v[146:147] op_sel_hi:[1,0,1]
	v_cvt_pk_bf16_f32 v244, v148, v149
	v_cvt_pk_bf16_f32 v245, v150, v151
	v_cvt_pk_bf16_f32 v246, v152, v153
	s_waitcnt vmcnt(6)
	s_nop 1
	v_mov_b32_e32 v230, v8
	v_mov_b32_e32 v231, v9
	v_mov_b32_e32 v232, v10
	v_mov_b32_e32 v233, v11
	v_lshlrev_b32_e32 v154, 16, v230
	v_cvt_pk_bf16_f32 v247, v146, v147
	v_and_b32_e32 v155, 0xffff0000, v230
	global_store_dwordx4 v[234:235], v[244:247], off nt
	v_lshlrev_b32_e32 v168, 16, v231
	v_and_b32_e32 v169, 0xffff0000, v231
	v_lshlrev_b32_e32 v172, 16, v232
	v_and_b32_e32 v173, 0xffff0000, v232
	v_lshlrev_b32_e32 v229, 16, v233
	v_and_b32_e32 v234, 0xffff0000, v233
	s_waitcnt lgkmcnt(0)
	v_sub_f32_e32 v155, v155, v160
	v_sub_f32_e32 v154, v154, v160
	v_sub_f32_e32 v231, v169, v160
	v_sub_f32_e32 v230, v168, v160
	v_sub_f32_e32 v233, v173, v160
	v_sub_f32_e32 v232, v172, v160
	v_sub_f32_e32 v235, v234, v160
	v_sub_f32_e32 v234, v229, v160
	v_pk_mul_f32 v[154:155], v[160:161], v[154:155] op_sel:[1,0]
	v_pk_mul_f32 v[232:233], v[160:161], v[232:233] op_sel:[1,0]
	v_pk_fma_f32 v[154:155], v[100:101], v[154:155], v[96:97]
	v_pk_fma_f32 v[232:233], v[104:105], v[232:233], v[108:109]
	v_pk_mul_f32 v[230:231], v[160:161], v[230:231] op_sel:[1,0]
	v_pk_mul_f32 v[234:235], v[160:161], v[234:235] op_sel:[1,0]
	v_pk_fma_f32 v[154:155], v[154:155], s[70:71], v[140:141] op_sel_hi:[1,0,1]
	v_pk_fma_f32 v[140:141], v[232:233], s[70:71], v[136:137] op_sel_hi:[1,0,1]
	v_pk_fma_f32 v[230:231], v[102:103], v[230:231], v[98:99]
	v_pk_fma_f32 v[234:235], v[106:107], v[234:235], v[110:111]
	v_pk_fma_f32 v[142:143], v[230:231], s[70:71], v[142:143] op_sel_hi:[1,0,1]
	v_pk_fma_f32 v[138:139], v[234:235], s[70:71], v[138:139] op_sel_hi:[1,0,1]
	v_cvt_pk_bf16_f32 v230, v154, v155
	v_cvt_pk_bf16_f32 v231, v142, v143
	v_cvt_pk_bf16_f32 v232, v140, v141
	s_waitcnt vmcnt(6)
	s_nop 1
	v_mov_b32_e32 v248, v12
	v_mov_b32_e32 v249, v13
	v_mov_b32_e32 v250, v14
	v_mov_b32_e32 v251, v15
	v_lshlrev_b32_e32 v168, 16, v248
	v_and_b32_e32 v169, 0xffff0000, v248
	v_lshlrev_b32_e32 v229, 16, v250
	v_and_b32_e32 v238, 0xffff0000, v250
	v_lshlrev_b32_e32 v172, 16, v249
	v_and_b32_e32 v173, 0xffff0000, v249
	v_sub_f32_e32 v245, v169, v162
	v_sub_f32_e32 v244, v168, v162
	v_sub_f32_e32 v249, v238, v162
	v_sub_f32_e32 v248, v229, v162
	v_lshlrev_b32_e32 v239, 16, v251
	v_and_b32_e32 v250, 0xffff0000, v251
	v_pk_mul_f32 v[244:245], v[162:163], v[244:245] op_sel:[1,0]
	v_pk_mul_f32 v[248:249], v[162:163], v[248:249] op_sel:[1,0]
	v_sub_f32_e32 v247, v173, v162
	v_sub_f32_e32 v246, v172, v162
	v_sub_f32_e32 v251, v250, v162
	v_sub_f32_e32 v250, v239, v162
	v_pk_fma_f32 v[136:137], v[100:101], v[244:245], v[96:97]
	v_pk_fma_f32 v[244:245], v[104:105], v[248:249], v[108:109]
	v_pk_mul_f32 v[246:247], v[162:163], v[246:247] op_sel:[1,0]
	v_pk_mul_f32 v[250:251], v[162:163], v[250:251] op_sel:[1,0]
	v_pk_fma_f32 v[132:133], v[136:137], s[70:71], v[132:133] op_sel_hi:[1,0,1]
	v_pk_fma_f32 v[136:137], v[244:245], s[70:71], v[128:129] op_sel_hi:[1,0,1]
	v_or_b32_e32 v128, 0x80, v196
	v_pk_fma_f32 v[234:235], v[102:103], v[246:247], v[98:99]
	v_pk_fma_f32 v[246:247], v[106:107], v[250:251], v[110:111]
	v_cvt_pk_bf16_f32 v233, v138, v139
	v_ashrrev_i32_e32 v129, 31, v128
	v_pk_fma_f32 v[134:135], v[234:235], s[70:71], v[134:135] op_sel_hi:[1,0,1]
	v_pk_fma_f32 v[130:131], v[246:247], s[70:71], v[130:131] op_sel_hi:[1,0,1]
	global_store_dwordx4 v[252:253], v[230:233], off nt
	v_lshlrev_b64 v[128:129], 1, v[128:129]
	v_mul_f32_e32 v253, v204, v204
	v_cvt_pk_bf16_f32 v230, v132, v133
	v_cvt_pk_bf16_f32 v231, v134, v135
	v_cvt_pk_bf16_f32 v232, v136, v137
	v_cvt_pk_bf16_f32 v233, v130, v131
	v_lshl_add_u64 v[208:209], s[42:43], 0, v[210:211]
	v_lshl_add_u64 v[208:209], v[208:209], 0, v[128:129]
	v_lshl_add_u64 v[210:211], s[42:43], 0, v[212:213]
	v_lshl_add_u64 v[212:213], s[42:43], 0, v[216:217]
	global_store_dwordx4 v[214:215], v[230:233], off nt
	v_lshl_add_u64 v[216:217], v[202:203], 0, v[128:129]
	v_lshl_add_u64 v[202:203], v[212:213], 0, v[128:129]
	v_lshl_add_u64 v[210:211], v[210:211], 0, v[128:129]
	s_waitcnt vmcnt(7)
	s_nop 1
	v_mov_b32_e32 v244, v16
	v_mov_b32_e32 v245, v17
	v_mov_b32_e32 v246, v18
	v_mov_b32_e32 v247, v19
	v_lshlrev_b32_e32 v168, 16, v244
	v_and_b32_e32 v169, 0xffff0000, v244
	v_lshlrev_b32_e32 v172, 16, v245
	v_and_b32_e32 v173, 0xffff0000, v245
	v_lshlrev_b32_e32 v229, 16, v246
	v_and_b32_e32 v230, 0xffff0000, v246
	v_lshlrev_b32_e32 v232, 16, v247
	v_and_b32_e32 v233, 0xffff0000, v247
	v_sub_f32_e32 v213, v169, v164
	v_sub_f32_e32 v212, v168, v164
	v_sub_f32_e32 v215, v173, v164
	v_sub_f32_e32 v214, v172, v164
	v_sub_f32_e32 v231, v230, v164
	v_sub_f32_e32 v230, v229, v164
	v_sub_f32_e32 v233, v233, v164
	v_sub_f32_e32 v232, v232, v164
	s_waitcnt vmcnt(6)
	s_nop 1
	v_mov_b32_e32 v248, v20
	v_mov_b32_e32 v249, v21
	v_mov_b32_e32 v250, v22
	v_mov_b32_e32 v251, v23
	v_lshlrev_b32_e32 v234, 16, v248
	v_and_b32_e32 v235, 0xffff0000, v248
	v_lshlrev_b32_e32 v238, 16, v249
	v_and_b32_e32 v239, 0xffff0000, v249
	v_lshlrev_b32_e32 v246, 16, v250
	v_and_b32_e32 v247, 0xffff0000, v250
	v_lshlrev_b32_e32 v248, 16, v251
	v_and_b32_e32 v249, 0xffff0000, v251
	v_pk_mul_f32 v[214:215], v[164:165], v[214:215] op_sel:[1,0]
	v_pk_mul_f32 v[212:213], v[164:165], v[212:213] op_sel:[1,0]
	v_pk_mul_f32 v[232:233], v[164:165], v[232:233] op_sel:[1,0]
	v_pk_mul_f32 v[164:165], v[164:165], v[230:231] op_sel:[1,0]
	v_sub_f32_e32 v235, v235, v166
	v_sub_f32_e32 v234, v234, v166
	v_sub_f32_e32 v245, v239, v166
	v_sub_f32_e32 v244, v238, v166
	v_sub_f32_e32 v247, v247, v166
	v_sub_f32_e32 v246, v246, v166
	v_sub_f32_e32 v249, v249, v166
	v_sub_f32_e32 v248, v248, v166
	v_pk_fma_f32 v[212:213], v[72:73], v[212:213], v[76:77]
	v_pk_fma_f32 v[214:215], v[74:75], v[214:215], v[78:79]
	v_pk_fma_f32 v[164:165], v[64:65], v[164:165], v[68:69]
	v_pk_fma_f32 v[232:233], v[66:67], v[232:233], v[70:71]
	v_pk_mul_f32 v[230:231], v[166:167], v[244:245] op_sel:[1,0]
	v_pk_mul_f32 v[234:235], v[166:167], v[234:235] op_sel:[1,0]
	v_pk_fma_f32 v[214:215], v[214:215], s[70:71], v[126:127] op_sel_hi:[1,0,1]
	v_pk_fma_f32 v[212:213], v[212:213], s[70:71], v[124:125] op_sel_hi:[1,0,1]
	v_pk_fma_f32 v[232:233], v[232:233], s[70:71], v[122:123] op_sel_hi:[1,0,1]
	v_pk_fma_f32 v[244:245], v[164:165], s[70:71], v[120:121] op_sel_hi:[1,0,1]
	v_cvt_pk_bf16_f32 v120, v212, v213
	v_cvt_pk_bf16_f32 v121, v214, v215
	v_pk_mul_f32 v[164:165], v[166:167], v[248:249] op_sel:[1,0]
	v_cvt_pk_bf16_f32 v122, v244, v245
	v_cvt_pk_bf16_f32 v123, v232, v233
	v_pk_mul_f32 v[166:167], v[166:167], v[246:247] op_sel:[1,0]
	v_pk_fma_f32 v[234:235], v[72:73], v[234:235], v[76:77]
	v_pk_fma_f32 v[230:231], v[74:75], v[230:231], v[78:79]
	v_pk_fma_f32 v[166:167], v[64:65], v[166:167], v[68:69]
	v_pk_fma_f32 v[164:165], v[66:67], v[164:165], v[70:71]
	v_pk_fma_f32 v[118:119], v[230:231], s[70:71], v[118:119] op_sel_hi:[1,0,1]
	v_pk_fma_f32 v[116:117], v[234:235], s[70:71], v[116:117] op_sel_hi:[1,0,1]
	v_pk_fma_f32 v[114:115], v[164:165], s[70:71], v[114:115] op_sel_hi:[1,0,1]
	v_pk_fma_f32 v[112:113], v[166:167], s[70:71], v[112:113] op_sel_hi:[1,0,1]
	global_store_dwordx4 v[216:217], v[120:123], off nt
	v_add_f32_e32 v230, v158, v159
	v_add_f32_e32 v246, v156, v157
	v_cvt_pk_bf16_f32 v120, v116, v117
	v_cvt_pk_bf16_f32 v121, v118, v119
	v_cvt_pk_bf16_f32 v122, v112, v113
	v_cvt_pk_bf16_f32 v123, v114, v115
	v_mul_f32_e32 v251, v158, v158
	global_store_dwordx4 v[208:209], v[120:123], off nt
	v_mul_f32_e32 v239, v156, v156
	v_add_f32_e32 v216, v206, v207
	v_mul_f32_e32 v249, v206, v206
	v_mul_f32_e32 v207, v207, v207
	v_mul_f32_e32 v159, v159, v159
	v_pk_mul_f32 v[172:173], v[232:233], v[232:233]
	v_pk_mul_f32 v[168:169], v[244:245], v[244:245]
	v_mov_b32_e32 v248, v212
	v_mov_b32_e32 v206, v213
	v_mov_b32_e32 v250, v214
	v_add_f32_e32 v234, v204, v205
	v_mul_f32_e32 v205, v205, v205
	v_mul_f32_e32 v157, v157, v157
	v_mul_f32_e32 v217, v212, v212
	v_mul_f32_e32 v231, v213, v213
	v_pk_mov_b32 v[212:213], v[168:169], v[172:173] op_sel:[1,0]
	v_mov_b32_e32 v169, v173
	v_mov_b32_e32 v252, v244
	v_mov_b32_e32 v204, v245
	v_mov_b32_e32 v238, v232
	v_pk_add_f32 v[168:169], v[212:213], v[168:169]
	v_mul_f32_e32 v235, v214, v214
	v_mul_f32_e32 v247, v215, v215
	v_pk_add_f32 v[168:169], v[168:169], v[168:169] op_sel_hi:[0,1]
	s_waitcnt vmcnt(7)
	s_nop 1
	v_mov_b32_e32 v124, v24
	v_mov_b32_e32 v125, v25
	v_mov_b32_e32 v126, v26
	v_mov_b32_e32 v127, v27
	v_lshlrev_b32_e32 v120, 16, v124
	v_and_b32_e32 v121, 0xffff0000, v124
	v_lshlrev_b32_e32 v122, 16, v125
	v_and_b32_e32 v123, 0xffff0000, v125
	v_lshlrev_b32_e32 v124, 16, v126
	v_and_b32_e32 v125, 0xffff0000, v126
	v_lshlrev_b32_e32 v126, 16, v127
	v_and_b32_e32 v127, 0xffff0000, v127
	v_sub_f32_e32 v121, v121, v160
	v_sub_f32_e32 v120, v120, v160
	v_sub_f32_e32 v123, v123, v160
	v_sub_f32_e32 v122, v122, v160
	v_sub_f32_e32 v125, v125, v160
	v_sub_f32_e32 v124, v124, v160
	v_sub_f32_e32 v127, v127, v160
	v_sub_f32_e32 v126, v126, v160
	v_pk_mul_f32 v[122:123], v[160:161], v[122:123] op_sel:[1,0]
	s_waitcnt vmcnt(6)
	s_nop 1
	v_mov_b32_e32 v164, v28
	v_mov_b32_e32 v165, v29
	v_mov_b32_e32 v166, v30
	v_mov_b32_e32 v167, v31
	v_lshlrev_b32_e32 v156, 16, v164
	v_and_b32_e32 v158, 0xffff0000, v164
	v_pk_mul_f32 v[120:121], v[160:161], v[120:121] op_sel:[1,0]
	v_pk_mul_f32 v[126:127], v[160:161], v[126:127] op_sel:[1,0]
	v_pk_mul_f32 v[124:125], v[160:161], v[124:125] op_sel:[1,0]
	v_sub_f32_e32 v161, v158, v162
	v_sub_f32_e32 v160, v156, v162
	v_pk_fma_f32 v[120:121], v[72:73], v[120:121], v[76:77]
	v_pk_fma_f32 v[122:123], v[74:75], v[122:123], v[78:79]
	v_pk_fma_f32 v[124:125], v[64:65], v[124:125], v[68:69]
	v_pk_fma_f32 v[126:127], v[66:67], v[126:127], v[70:71]
	v_pk_mul_f32 v[160:161], v[162:163], v[160:161] op_sel:[1,0]
	v_pk_fma_f32 v[94:95], v[122:123], s[70:71], v[94:95] op_sel_hi:[1,0,1]
	v_pk_fma_f32 v[92:93], v[120:121], s[70:71], v[92:93] op_sel_hi:[1,0,1]
	v_pk_fma_f32 v[90:91], v[126:127], s[70:71], v[90:91] op_sel_hi:[1,0,1]
	v_pk_fma_f32 v[88:89], v[124:125], s[70:71], v[88:89] op_sel_hi:[1,0,1]
	v_cvt_pk_bf16_f32 v120, v92, v93
	v_cvt_pk_bf16_f32 v121, v94, v95
	v_mov_b32_e32 v158, v215
	v_cvt_pk_bf16_f32 v122, v88, v89
	v_cvt_pk_bf16_f32 v123, v90, v91
	v_pk_fma_f32 v[124:125], v[72:73], v[160:161], v[76:77]
	global_store_dwordx4 v[210:211], v[120:123], off nt
	v_mov_b32_e32 v156, v233
	v_pk_fma_f32 v[84:85], v[124:125], s[70:71], v[84:85] op_sel_hi:[1,0,1]
	v_pk_add_f32 v[120:121], v[248:249], v[206:207]
	v_pk_add_f32 v[122:123], v[250:251], v[158:159]
	v_pk_add_f32 v[124:125], v[238:239], v[156:157]
	v_pk_add_f32 v[120:121], v[120:121], v[122:123]
	v_pk_add_f32 v[122:123], v[252:253], v[204:205]
	v_lshlrev_b32_e32 v168, 16, v166
	v_pk_add_f32 v[122:123], v[122:123], v[124:125]
	v_and_b32_e32 v166, 0xffff0000, v166
	v_pk_add_f32 v[120:121], v[120:121], v[122:123]
	v_pk_add_f32 v[122:123], v[216:217], v[230:231]
	v_pk_add_f32 v[124:125], v[234:235], v[246:247]
	v_lshlrev_b32_e32 v172, 16, v167
	v_and_b32_e32 v173, 0xffff0000, v167
	v_sub_f32_e32 v167, v166, v162
	v_sub_f32_e32 v166, v168, v162
	v_pk_add_f32 v[122:123], v[122:123], v[124:125]
	v_mov_b32_e32 v168, v175
	v_pk_add_f32 v[122:123], v[122:123], v[168:169]
	v_lshlrev_b32_e32 v164, 16, v165
	v_pk_add_f32 v[120:121], v[120:121], v[122:123]
	ds_bpermute_b32 v122, v225, v120
	ds_bpermute_b32 v123, v225, v121
	v_and_b32_e32 v165, 0xffff0000, v165
	v_sub_f32_e32 v165, v165, v162
	v_sub_f32_e32 v164, v164, v162
	v_sub_f32_e32 v173, v173, v162
	s_waitcnt lgkmcnt(0)
	v_pk_add_f32 v[120:121], v[120:121], v[122:123]
	ds_bpermute_b32 v122, v226, v120
	ds_bpermute_b32 v123, v226, v121
	v_sub_f32_e32 v172, v172, v162
	v_pk_mul_f32 v[164:165], v[162:163], v[164:165] op_sel:[1,0]
	v_pk_mul_f32 v[172:173], v[162:163], v[172:173] op_sel:[1,0]
	v_pk_mul_f32 v[162:163], v[162:163], v[166:167] op_sel:[1,0]
	v_pk_fma_f32 v[126:127], v[74:75], v[164:165], v[78:79]
	v_pk_fma_f32 v[160:161], v[64:65], v[162:163], v[68:69]
	v_pk_fma_f32 v[124:125], v[66:67], v[172:173], v[70:71]
	v_pk_fma_f32 v[86:87], v[126:127], s[70:71], v[86:87] op_sel_hi:[1,0,1]
	v_pk_fma_f32 v[82:83], v[124:125], s[70:71], v[82:83] op_sel_hi:[1,0,1]
	v_pk_fma_f32 v[80:81], v[160:161], s[70:71], v[80:81] op_sel_hi:[1,0,1]
	v_cvt_pk_bf16_f32 v124, v84, v85
	v_cvt_pk_bf16_f32 v125, v86, v87
	s_nop 0
	v_cvt_pk_bf16_f32 v126, v80, v81
	v_cvt_pk_bf16_f32 v127, v82, v83
	global_store_dwordx4 v[202:203], v[124:127], off nt
	s_and_saveexec_b64 s[10:11], s[22:23]
	s_cbranch_execz .LBB0_1354
	v_lshlrev_b64 v[124:125], 7, v[192:193]
	v_lshl_add_u64 v[124:125], s[44:45], 0, v[124:125]
	s_waitcnt lgkmcnt(0)
	v_pk_add_f32 v[120:121], v[120:121], v[122:123]
	global_store_dwordx2 v[124:125], v[120:121], off

.LBB0_1360:
	s_or_b64 exec, exec, s[10:11]
	v_add_u32_e32 v94, 0x80, v192
	v_ashrrev_i32_e32 v95, 31, v94
	v_lshlrev_b64 v[118:119], 11, v[94:95]
	v_add_u32_e32 v90, 0x90, v192
	v_lshl_add_u64 v[112:113], s[42:43], 0, v[118:119]
	v_ashrrev_i32_e32 v91, 31, v90
	v_lshl_add_u64 v[114:115], v[196:197], 1, v[112:113]
	v_lshlrev_b64 v[116:117], 11, v[90:91]
	v_lshl_add_u32 v86, v237, 4, s47
	v_add_u32_e32 v87, 0x10000, v86
	ds_read_b128 v[0:3], v86 offset:49152
	ds_read_b128 v[4:7], v86 offset:57344
	ds_read_b128 v[8:11], v87
	ds_read_b128 v[12:15], v87 offset:8192
	ds_read_b128 v[16:19], v86
	ds_read_b128 v[20:23], v86 offset:8192
	ds_read_b128 v[24:27], v87 offset:16384
	ds_read_b128 v[28:31], v87 offset:24576
	s_mov_b32 s101, 0
	s_mov_b32 s100, 0x8000
	v_lshl_add_u64 v[80:81], v[114:115], 0, s[100:101]
	s_mov_b32 s100, 0x10000
	v_lshl_add_u64 v[82:83], v[114:115], 0, s[100:101]
	s_mov_b32 s100, 0x18000
	v_lshl_add_u64 v[84:85], v[114:115], 0, s[100:101]
	global_load_dwordx4 v[156:159], v[114:115], off
	global_load_dwordx4 v[160:163], v[80:81], off
	global_load_dwordx4 v[164:167], v[82:83], off
	global_load_dwordx4 v[196:199], v[84:85], off
	global_load_dwordx4 v[200:203], v[114:115], off offset:256
	global_load_dwordx4 v[204:207], v[80:81], off offset:256
	global_load_dwordx4 v[208:211], v[82:83], off offset:256
	global_load_dwordx4 v[212:215], v[84:85], off offset:256
	s_waitcnt lgkmcnt(0)
	v_lshl_add_u64 v[124:125], v[194:195], 0, v[116:117]
	ds_read2_b64 v[84:87], v228 offset0:128 offset1:144
	s_waitcnt lgkmcnt(1)
	ds_read2_b64 v[80:83], v228 offset0:160 offset1:176
	v_add_u32_e32 v92, 0xa0, v192
	v_ashrrev_i32_e32 v93, 31, v92
	v_lshl_add_u64 v[126:127], v[194:195], 0, v[118:119]
	v_add_u32_e32 v88, 0xb0, v192
	v_lshlrev_b64 v[122:123], 11, v[92:93]
	v_ashrrev_i32_e32 v89, 31, v88
	v_lshl_add_u64 v[138:139], v[194:195], 0, v[122:123]
	v_lshlrev_b64 v[120:121], 11, v[88:89]
	v_lshl_add_u64 v[118:119], v[194:195], 0, v[120:121]
	v_lshl_add_u64 v[112:113], v[112:113], 0, v[128:129]
	s_waitcnt vmcnt(7)
	s_nop 1
	v_mov_b32_e32 v130, v156
	v_mov_b32_e32 v131, v157
	v_mov_b32_e32 v132, v158
	v_mov_b32_e32 v133, v159
	v_lshlrev_b32_e32 v140, 16, v130
	v_and_b32_e32 v130, 0xffff0000, v130
	v_lshlrev_b32_e32 v141, 16, v131
	v_and_b32_e32 v142, 0xffff0000, v131
	v_lshlrev_b32_e32 v143, 16, v132
	v_and_b32_e32 v144, 0xffff0000, v132
	v_lshlrev_b32_e32 v145, 16, v133
	v_and_b32_e32 v146, 0xffff0000, v133
	s_waitcnt vmcnt(6)
	s_nop 1
	v_mov_b32_e32 v134, v160
	v_mov_b32_e32 v135, v161
	v_mov_b32_e32 v136, v162
	v_mov_b32_e32 v137, v163
	v_lshlrev_b32_e32 v147, 16, v134
	v_and_b32_e32 v148, 0xffff0000, v134
	v_lshlrev_b32_e32 v149, 16, v135
	v_and_b32_e32 v150, 0xffff0000, v135
	v_lshlrev_b32_e32 v151, 16, v136
	v_and_b32_e32 v152, 0xffff0000, v136
	v_lshlrev_b32_e32 v153, 16, v137
	v_and_b32_e32 v154, 0xffff0000, v137
	s_waitcnt lgkmcnt(1)
	v_sub_f32_e32 v131, v130, v84
	v_sub_f32_e32 v130, v140, v84
	v_sub_f32_e32 v133, v142, v84
	v_sub_f32_e32 v132, v141, v84
	v_sub_f32_e32 v135, v144, v84
	v_sub_f32_e32 v134, v143, v84
	v_sub_f32_e32 v137, v146, v84
	v_sub_f32_e32 v136, v145, v84
	v_pk_mul_f32 v[132:133], v[84:85], v[132:133] op_sel:[1,0]
	v_pk_mul_f32 v[130:131], v[84:85], v[130:131] op_sel:[1,0]
	v_pk_mul_f32 v[136:137], v[84:85], v[136:137] op_sel:[1,0]
	v_pk_mul_f32 v[134:135], v[84:85], v[134:135] op_sel:[1,0]
	v_pk_fma_f32 v[130:131], v[100:101], v[130:131], v[96:97]
	v_pk_fma_f32 v[132:133], v[102:103], v[132:133], v[98:99]
	v_pk_fma_f32 v[134:135], v[104:105], v[134:135], v[108:109]
	v_pk_fma_f32 v[136:137], v[106:107], v[136:137], v[110:111]
	v_sub_f32_e32 v141, v148, v86
	v_sub_f32_e32 v140, v147, v86
	v_sub_f32_e32 v143, v150, v86
	v_sub_f32_e32 v142, v149, v86
	v_sub_f32_e32 v145, v152, v86
	v_sub_f32_e32 v144, v151, v86
	v_pk_fma_f32 v[62:63], v[132:133], s[70:71], v[62:63] op_sel_hi:[1,0,1]
	v_pk_fma_f32 v[60:61], v[130:131], s[70:71], v[60:61] op_sel_hi:[1,0,1]
	v_pk_fma_f32 v[58:59], v[136:137], s[70:71], v[58:59] op_sel_hi:[1,0,1]
	v_pk_fma_f32 v[56:57], v[134:135], s[70:71], v[56:57] op_sel_hi:[1,0,1]
	v_cvt_pk_bf16_f32 v130, v60, v61
	v_cvt_pk_bf16_f32 v131, v62, v63
	v_pk_mul_f32 v[134:135], v[86:87], v[142:143] op_sel:[1,0]
	v_cvt_pk_bf16_f32 v132, v56, v57
	v_cvt_pk_bf16_f32 v133, v58, v59
	global_store_dwordx4 v[126:127], v[130:133], off nt
	v_sub_f32_e32 v127, v154, v86
	v_sub_f32_e32 v126, v153, v86
	v_pk_mul_f32 v[136:137], v[86:87], v[140:141] op_sel:[1,0]
	v_pk_mul_f32 v[126:127], v[86:87], v[126:127] op_sel:[1,0]
	v_pk_mul_f32 v[140:141], v[86:87], v[144:145] op_sel:[1,0]
	v_pk_fma_f32 v[136:137], v[100:101], v[136:137], v[96:97]
	v_pk_fma_f32 v[134:135], v[102:103], v[134:135], v[98:99]
	v_pk_fma_f32 v[140:141], v[104:105], v[140:141], v[108:109]
	v_pk_fma_f32 v[126:127], v[106:107], v[126:127], v[110:111]
	v_pk_fma_f32 v[54:55], v[134:135], s[70:71], v[54:55] op_sel_hi:[1,0,1]
	v_pk_fma_f32 v[52:53], v[136:137], s[70:71], v[52:53] op_sel_hi:[1,0,1]
	v_pk_fma_f32 v[50:51], v[126:127], s[70:71], v[50:51] op_sel_hi:[1,0,1]
	v_pk_fma_f32 v[48:49], v[140:141], s[70:71], v[48:49] op_sel_hi:[1,0,1]
	v_cvt_pk_bf16_f32 v134, v52, v53
	v_cvt_pk_bf16_f32 v135, v54, v55
	s_waitcnt vmcnt(6)
	s_nop 1
	v_mov_b32_e32 v130, v164
	v_mov_b32_e32 v131, v165
	v_mov_b32_e32 v132, v166
	v_mov_b32_e32 v133, v167
	v_and_b32_e32 v140, 0xffff0000, v132
	v_cvt_pk_bf16_f32 v136, v48, v49
	v_cvt_pk_bf16_f32 v137, v50, v51
	global_store_dwordx4 v[124:125], v[134:137], off nt
	v_lshlrev_b32_e32 v141, 16, v133
	v_lshlrev_b32_e32 v134, 16, v130
	v_and_b32_e32 v130, 0xffff0000, v130
	v_lshlrev_b32_e32 v135, 16, v131
	v_and_b32_e32 v136, 0xffff0000, v131
	v_lshlrev_b32_e32 v137, 16, v132
	v_and_b32_e32 v142, 0xffff0000, v133
	s_waitcnt lgkmcnt(0)
	v_sub_f32_e32 v131, v130, v80
	v_sub_f32_e32 v130, v134, v80
	v_sub_f32_e32 v133, v136, v80
	v_sub_f32_e32 v132, v135, v80
	v_sub_f32_e32 v135, v140, v80
	v_sub_f32_e32 v134, v137, v80
	v_sub_f32_e32 v137, v142, v80
	v_sub_f32_e32 v136, v141, v80
	v_pk_mul_f32 v[132:133], v[80:81], v[132:133] op_sel:[1,0]
	v_pk_mul_f32 v[130:131], v[80:81], v[130:131] op_sel:[1,0]
	v_pk_mul_f32 v[136:137], v[80:81], v[136:137] op_sel:[1,0]
	v_pk_mul_f32 v[134:135], v[80:81], v[134:135] op_sel:[1,0]
	s_waitcnt vmcnt(6)
	s_nop 1
	v_mov_b32_e32 v124, v196
	v_mov_b32_e32 v125, v197
	v_mov_b32_e32 v126, v198
	v_mov_b32_e32 v127, v199
	v_lshlrev_b32_e32 v140, 16, v124
	v_and_b32_e32 v141, 0xffff0000, v124
	v_lshlrev_b32_e32 v142, 16, v125
	v_and_b32_e32 v143, 0xffff0000, v125
	v_lshlrev_b32_e32 v144, 16, v126
	v_and_b32_e32 v145, 0xffff0000, v126
	v_lshlrev_b32_e32 v146, 16, v127
	v_and_b32_e32 v147, 0xffff0000, v127
	v_pk_fma_f32 v[124:125], v[100:101], v[130:131], v[96:97]
	v_pk_fma_f32 v[126:127], v[102:103], v[132:133], v[98:99]
	v_pk_fma_f32 v[130:131], v[104:105], v[134:135], v[108:109]
	v_pk_fma_f32 v[132:133], v[106:107], v[136:137], v[110:111]
	v_sub_f32_e32 v135, v141, v82
	v_sub_f32_e32 v134, v140, v82
	v_sub_f32_e32 v137, v143, v82
	v_sub_f32_e32 v136, v142, v82
	v_sub_f32_e32 v141, v145, v82
	v_sub_f32_e32 v140, v144, v82
	v_sub_f32_e32 v143, v147, v82
	v_sub_f32_e32 v142, v146, v82
	v_pk_fma_f32 v[42:43], v[132:133], s[70:71], v[42:43] op_sel_hi:[1,0,1]
	v_pk_fma_f32 v[40:41], v[130:131], s[70:71], v[40:41] op_sel_hi:[1,0,1]
	v_pk_mul_f32 v[130:131], v[82:83], v[136:137] op_sel:[1,0]
	v_pk_mul_f32 v[132:133], v[82:83], v[134:135] op_sel:[1,0]
	v_pk_mul_f32 v[134:135], v[82:83], v[142:143] op_sel:[1,0]
	v_pk_mul_f32 v[136:137], v[82:83], v[140:141] op_sel:[1,0]
	v_pk_fma_f32 v[96:97], v[100:101], v[132:133], v[96:97]
	v_pk_fma_f32 v[98:99], v[102:103], v[130:131], v[98:99]
	v_pk_fma_f32 v[100:101], v[104:105], v[136:137], v[108:109]
	v_pk_fma_f32 v[102:103], v[106:107], v[134:135], v[110:111]
	v_pk_fma_f32 v[46:47], v[126:127], s[70:71], v[46:47] op_sel_hi:[1,0,1]
	v_pk_fma_f32 v[44:45], v[124:125], s[70:71], v[44:45] op_sel_hi:[1,0,1]
	v_pk_fma_f32 v[38:39], v[98:99], s[70:71], v[38:39] op_sel_hi:[1,0,1]
	v_cvt_pk_bf16_f32 v124, v44, v45
	v_cvt_pk_bf16_f32 v125, v46, v47
	v_cvt_pk_bf16_f32 v126, v40, v41
	v_cvt_pk_bf16_f32 v127, v42, v43
	global_store_dwordx4 v[138:139], v[124:127], off nt
	v_pk_fma_f32 v[36:37], v[96:97], s[70:71], v[36:37] op_sel_hi:[1,0,1]
	v_pk_fma_f32 v[34:35], v[102:103], s[70:71], v[34:35] op_sel_hi:[1,0,1]
	v_pk_fma_f32 v[32:33], v[100:101], s[70:71], v[32:33] op_sel_hi:[1,0,1]
	v_cvt_pk_bf16_f32 v100, v36, v37
	v_cvt_pk_bf16_f32 v101, v38, v39
	v_lshl_add_u64 v[96:97], s[42:43], 0, v[116:117]
	v_cvt_pk_bf16_f32 v102, v32, v33
	v_cvt_pk_bf16_f32 v103, v34, v35
	v_lshl_add_u64 v[114:115], v[96:97], 0, v[128:129]
	v_lshl_add_u64 v[96:97], s[42:43], 0, v[122:123]
	global_store_dwordx4 v[118:119], v[100:103], off nt
	v_lshl_add_u64 v[116:117], s[42:43], 0, v[120:121]
	v_lshl_add_u64 v[98:99], v[96:97], 0, v[128:129]
	v_lshl_add_u64 v[96:97], v[116:117], 0, v[128:129]
	s_waitcnt vmcnt(7)
	s_nop 1
	v_mov_b32_e32 v104, v200
	v_mov_b32_e32 v105, v201
	v_mov_b32_e32 v106, v202
	v_mov_b32_e32 v107, v203
	v_lshlrev_b32_e32 v100, 16, v104
	v_and_b32_e32 v101, 0xffff0000, v104
	v_lshlrev_b32_e32 v102, 16, v105
	v_and_b32_e32 v103, 0xffff0000, v105
	v_lshlrev_b32_e32 v104, 16, v106
	v_and_b32_e32 v105, 0xffff0000, v106
	v_lshlrev_b32_e32 v106, 16, v107
	v_and_b32_e32 v107, 0xffff0000, v107
	v_sub_f32_e32 v101, v101, v84
	v_sub_f32_e32 v100, v100, v84
	v_sub_f32_e32 v103, v103, v84
	v_sub_f32_e32 v102, v102, v84
	v_sub_f32_e32 v105, v105, v84
	v_sub_f32_e32 v104, v104, v84
	v_sub_f32_e32 v107, v107, v84
	v_sub_f32_e32 v106, v106, v84
	v_pk_mul_f32 v[102:103], v[84:85], v[102:103] op_sel:[1,0]
	v_pk_mul_f32 v[100:101], v[84:85], v[100:101] op_sel:[1,0]
	v_pk_mul_f32 v[106:107], v[84:85], v[106:107] op_sel:[1,0]
	v_pk_mul_f32 v[84:85], v[84:85], v[104:105] op_sel:[1,0]
	v_pk_fma_f32 v[100:101], v[72:73], v[100:101], v[76:77]
	v_pk_fma_f32 v[102:103], v[74:75], v[102:103], v[78:79]
	v_pk_fma_f32 v[84:85], v[64:65], v[84:85], v[68:69]
	s_waitcnt vmcnt(6)
	s_nop 1
	v_mov_b32_e32 v108, v204
	v_mov_b32_e32 v109, v205
	v_mov_b32_e32 v110, v206
	v_mov_b32_e32 v111, v207
	v_lshlrev_b32_e32 v116, 16, v108
	v_and_b32_e32 v108, 0xffff0000, v108
	v_lshlrev_b32_e32 v117, 16, v109
	v_and_b32_e32 v118, 0xffff0000, v109
	v_lshlrev_b32_e32 v119, 16, v110
	v_and_b32_e32 v120, 0xffff0000, v110
	v_lshlrev_b32_e32 v121, 16, v111
	v_and_b32_e32 v122, 0xffff0000, v111
	v_pk_fma_f32 v[104:105], v[66:67], v[106:107], v[70:71]
	v_pk_fma_f32 v[102:103], v[102:103], s[70:71], v[30:31] op_sel_hi:[1,0,1]
	v_pk_fma_f32 v[100:101], v[100:101], s[70:71], v[28:29] op_sel_hi:[1,0,1]
	v_pk_fma_f32 v[106:107], v[84:85], s[70:71], v[24:25] op_sel_hi:[1,0,1]
	v_cvt_pk_bf16_f32 v24, v100, v101
	v_cvt_pk_bf16_f32 v25, v102, v103
	v_sub_f32_e32 v109, v108, v86
	v_sub_f32_e32 v108, v116, v86
	v_sub_f32_e32 v111, v118, v86
	v_sub_f32_e32 v110, v117, v86
	v_sub_f32_e32 v117, v120, v86
	v_sub_f32_e32 v116, v119, v86
	v_pk_fma_f32 v[104:105], v[104:105], s[70:71], v[26:27] op_sel_hi:[1,0,1]
	v_cvt_pk_bf16_f32 v26, v106, v107
	v_pk_mul_f32 v[84:85], v[86:87], v[108:109] op_sel:[1,0]
	v_cvt_pk_bf16_f32 v27, v104, v105
	global_store_dwordx4 v[112:113], v[24:27], off nt
	v_pk_fma_f32 v[84:85], v[72:73], v[84:85], v[76:77]
	v_sub_f32_e32 v25, v122, v86
	v_sub_f32_e32 v24, v121, v86
	v_pk_mul_f32 v[26:27], v[86:87], v[110:111] op_sel:[1,0]
	v_pk_mul_f32 v[24:25], v[86:87], v[24:25] op_sel:[1,0]
	v_pk_mul_f32 v[86:87], v[86:87], v[116:117] op_sel:[1,0]
	v_pk_fma_f32 v[26:27], v[74:75], v[26:27], v[78:79]
	v_pk_fma_f32 v[86:87], v[64:65], v[86:87], v[68:69]
	v_pk_fma_f32 v[24:25], v[66:67], v[24:25], v[70:71]
	v_pk_fma_f32 v[22:23], v[26:27], s[70:71], v[22:23] op_sel_hi:[1,0,1]
	v_pk_fma_f32 v[20:21], v[84:85], s[70:71], v[20:21] op_sel_hi:[1,0,1]
	v_pk_fma_f32 v[18:19], v[24:25], s[70:71], v[18:19] op_sel_hi:[1,0,1]
	v_pk_fma_f32 v[16:17], v[86:87], s[70:71], v[16:17] op_sel_hi:[1,0,1]
	v_cvt_pk_bf16_f32 v24, v20, v21
	v_cvt_pk_bf16_f32 v25, v22, v23
	v_pk_mul_f32 v[120:121], v[104:105], v[104:105]
	v_cvt_pk_bf16_f32 v26, v16, v17
	v_cvt_pk_bf16_f32 v27, v18, v19
	global_store_dwordx4 v[114:115], v[24:27], off nt
	v_pk_mul_f32 v[122:123], v[106:107], v[106:107]
	v_add_f32_e32 v24, v60, v61
	v_add_f32_e32 v26, v62, v63
	v_add_f32_e32 v108, v56, v57
	v_add_f32_e32 v110, v58, v59
	v_mul_f32_e32 v113, v60, v60
	v_mul_f32_e32 v25, v100, v100
	v_mul_f32_e32 v27, v101, v101
	v_mul_f32_e32 v109, v102, v102
	v_mul_f32_e32 v111, v103, v103
	v_mov_b32_e32 v112, v100
	v_mov_b32_e32 v60, v101
	v_pk_mov_b32 v[100:101], v[122:123], v[120:121] op_sel:[1,0]
	v_mov_b32_e32 v123, v121
	v_mul_f32_e32 v61, v61, v61
	v_mul_f32_e32 v115, v62, v62
	v_mul_f32_e32 v63, v63, v63
	v_mul_f32_e32 v117, v56, v56
	v_mul_f32_e32 v57, v57, v57
	v_mul_f32_e32 v119, v58, v58
	v_mul_f32_e32 v59, v59, v59
	v_mov_b32_e32 v114, v102
	v_mov_b32_e32 v62, v103
	v_mov_b32_e32 v116, v106
	v_mov_b32_e32 v56, v107
	v_mov_b32_e32 v118, v104
	v_mov_b32_e32 v58, v105
	v_pk_add_f32 v[24:25], v[24:25], v[26:27]
	v_pk_add_f32 v[26:27], v[108:109], v[110:111]
	v_pk_add_f32 v[100:101], v[100:101], v[122:123]
	v_pk_add_f32 v[60:61], v[112:113], v[60:61]
	v_pk_add_f32 v[62:63], v[114:115], v[62:63]
	v_pk_add_f32 v[56:57], v[116:117], v[56:57]
	v_pk_add_f32 v[58:59], v[118:119], v[58:59]
	v_pk_add_f32 v[24:25], v[24:25], v[26:27]
	v_pk_add_f32 v[26:27], v[100:101], v[100:101] op_sel_hi:[0,1]
	v_pk_add_f32 v[60:61], v[60:61], v[62:63]
	v_pk_add_f32 v[56:57], v[56:57], v[58:59]
	v_mov_b32_e32 v26, v175
	v_pk_add_f32 v[56:57], v[60:61], v[56:57]
	v_pk_add_f32 v[24:25], v[24:25], v[26:27]
	s_waitcnt vmcnt(7)
	s_nop 1
	v_mov_b32_e32 v28, v208
	v_mov_b32_e32 v29, v209
	v_mov_b32_e32 v30, v210
	v_mov_b32_e32 v31, v211
	v_and_b32_e32 v58, 0xffff0000, v29
	v_pk_add_f32 v[24:25], v[56:57], v[24:25]
	ds_bpermute_b32 v26, v225, v24
	ds_bpermute_b32 v27, v225, v25
	v_lshlrev_b32_e32 v56, 16, v28
	v_and_b32_e32 v28, 0xffff0000, v28
	v_lshlrev_b32_e32 v57, 16, v29
	v_lshlrev_b32_e32 v59, 16, v30
	v_and_b32_e32 v60, 0xffff0000, v30
	v_lshlrev_b32_e32 v61, 16, v31
	v_and_b32_e32 v62, 0xffff0000, v31
	s_waitcnt lgkmcnt(0)
	v_pk_add_f32 v[24:25], v[24:25], v[26:27]
	v_sub_f32_e32 v29, v28, v80
	v_sub_f32_e32 v28, v56, v80
	v_sub_f32_e32 v31, v58, v80
	v_sub_f32_e32 v30, v57, v80
	v_sub_f32_e32 v57, v60, v80
	v_sub_f32_e32 v56, v59, v80
	v_sub_f32_e32 v59, v62, v80
	v_sub_f32_e32 v58, v61, v80
	ds_bpermute_b32 v26, v226, v24
	ds_bpermute_b32 v27, v226, v25
	v_pk_mul_f32 v[30:31], v[80:81], v[30:31] op_sel:[1,0]
	v_pk_mul_f32 v[28:29], v[80:81], v[28:29] op_sel:[1,0]
	v_pk_mul_f32 v[58:59], v[80:81], v[58:59] op_sel:[1,0]
	v_pk_mul_f32 v[56:57], v[80:81], v[56:57] op_sel:[1,0]
	s_waitcnt vmcnt(6)
	s_nop 1
	v_mov_b32_e32 v84, v212
	v_mov_b32_e32 v85, v213
	v_mov_b32_e32 v86, v214
	v_mov_b32_e32 v87, v215
	v_lshlrev_b32_e32 v60, 16, v84
	v_and_b32_e32 v61, 0xffff0000, v84
	v_lshlrev_b32_e32 v62, 16, v85
	v_and_b32_e32 v63, 0xffff0000, v85
	v_lshlrev_b32_e32 v80, 16, v86
	v_and_b32_e32 v81, 0xffff0000, v86
	v_lshlrev_b32_e32 v84, 16, v87
	v_and_b32_e32 v85, 0xffff0000, v87
	v_pk_fma_f32 v[56:57], v[64:65], v[56:57], v[68:69]
	v_pk_fma_f32 v[58:59], v[66:67], v[58:59], v[70:71]
	v_sub_f32_e32 v61, v61, v82
	v_sub_f32_e32 v60, v60, v82
	v_sub_f32_e32 v63, v63, v82
	v_sub_f32_e32 v62, v62, v82
	v_sub_f32_e32 v81, v81, v82
	v_sub_f32_e32 v80, v80, v82
	v_sub_f32_e32 v85, v85, v82
	v_sub_f32_e32 v84, v84, v82
	v_pk_fma_f32 v[10:11], v[58:59], s[70:71], v[10:11] op_sel_hi:[1,0,1]
	v_pk_fma_f32 v[8:9], v[56:57], s[70:71], v[8:9] op_sel_hi:[1,0,1]
	v_pk_mul_f32 v[56:57], v[82:83], v[62:63] op_sel:[1,0]
	v_pk_mul_f32 v[58:59], v[82:83], v[60:61] op_sel:[1,0]
	v_pk_mul_f32 v[60:61], v[82:83], v[84:85] op_sel:[1,0]
	v_pk_mul_f32 v[62:63], v[82:83], v[80:81] op_sel:[1,0]
	v_pk_fma_f32 v[28:29], v[72:73], v[28:29], v[76:77]
	v_pk_fma_f32 v[30:31], v[74:75], v[30:31], v[78:79]
	v_pk_fma_f32 v[58:59], v[72:73], v[58:59], v[76:77]
	v_pk_fma_f32 v[56:57], v[74:75], v[56:57], v[78:79]
	v_pk_fma_f32 v[62:63], v[64:65], v[62:63], v[68:69]
	v_pk_fma_f32 v[60:61], v[66:67], v[60:61], v[70:71]
	v_pk_fma_f32 v[14:15], v[30:31], s[70:71], v[14:15] op_sel_hi:[1,0,1]
	v_pk_fma_f32 v[12:13], v[28:29], s[70:71], v[12:13] op_sel_hi:[1,0,1]
	v_pk_fma_f32 v[6:7], v[56:57], s[70:71], v[6:7] op_sel_hi:[1,0,1]
	v_cvt_pk_bf16_f32 v28, v12, v13
	v_cvt_pk_bf16_f32 v29, v14, v15
	v_cvt_pk_bf16_f32 v30, v8, v9
	v_cvt_pk_bf16_f32 v31, v10, v11
	v_pk_fma_f32 v[4:5], v[58:59], s[70:71], v[4:5] op_sel_hi:[1,0,1]
	v_pk_fma_f32 v[2:3], v[60:61], s[70:71], v[2:3] op_sel_hi:[1,0,1]
	v_pk_fma_f32 v[0:1], v[62:63], s[70:71], v[0:1] op_sel_hi:[1,0,1]
	global_store_dwordx4 v[98:99], v[28:31], off nt
	s_nop 1
	v_cvt_pk_bf16_f32 v28, v4, v5
	v_cvt_pk_bf16_f32 v29, v6, v7
	v_cvt_pk_bf16_f32 v30, v0, v1
	v_cvt_pk_bf16_f32 v31, v2, v3
	global_store_dwordx4 v[96:97], v[28:31], off nt
	s_and_saveexec_b64 s[10:11], s[22:23]
	s_cbranch_execz .LBB0_1362
	v_lshlrev_b64 v[28:29], 7, v[94:95]
	v_lshl_add_u64 v[28:29], s[44:45], 0, v[28:29]
	s_waitcnt lgkmcnt(0)
	v_pk_add_f32 v[24:25], v[24:25], v[26:27]
	global_store_dwordx2 v[28:29], v[24:25], off
